# GEMM K-loops: the last fragment ds_read of each burst moved into the m0 wait-state slot (24 s_nop removed)
# baseline (speedup 1.0000x reference)
; #define PG8_STAGE(bufoff, gbase, voff) do { _Pragma("unroll") for (int _i = 0; _i < 2; ++_i) \
;         __builtin_amdgcn_global_load_lds((const unsigned*)((const char*)(gbase) + (voff)[_i]), (PG8_LAS unsigned*)(lds + (bufoff) + ldsw + _i * 8192), 16, 0, 0); } while (0)
; #define PG8_LDA(dst, b, h) do { _Pragma("unroll") for (int m = 0; m < 4; ++m) _Pragma("unroll") for (int k = 0; k < 2; ++k) dst[m][k] = *(const PG8_LAS bf16x8*)(lds + PG8_SA(b, h) + aoff + m * 2048 + k * 1024); } while (0)
; #define PG8_LDB(dst, b, h) do { _Pragma("unroll") for (int n = 0; n < 2; ++n) _Pragma("unroll") for (int k = 0; k < 2; ++k) dst[n][k] = *(const PG8_LAS bf16x8*)(lds + PG8_SB(b, h) + boff + n * 2048 + k * 1024); } while (0)
; #define PG8_MMA(ai, bj, At, Bt) do { __builtin_amdgcn_s_setprio(1); _Pragma("unroll") for (int m = 0; m < 4; ++m) _Pragma("unroll") for (int n = 0; n < 2; ++n) _Pragma("unroll") for (int k = 0; k < 2; ++k) \
;         acc[ai][bj][m][n] = __builtin_amdgcn_mfma_f32_16x16x32_bf16(Bt[n][k], At[m][k], acc[ai][bj][m][n], 0, 0, 0); __builtin_amdgcn_s_setprio(0); } while (0)
; #define PG8_WAIT_V(n) asm volatile("s_waitcnt vmcnt(" #n ")" ::: "memory")
; template <class Epi, class Sched>
; __device__ __forceinline__ void gemm_phase(PG8_LAS unsigned char* lds, const Gemm g, const Sched& S, const Epi& E) {
;     ...
;         for (int t = 0; t < nt; t += 2) {
;             const bool last = (t == nt - 2);
;             const char* a1 = cA + (size_t)(t + 1) * kstep;
;             const char* a2 = last ? nA : cA + (size_t)(t + 2) * kstep; const char* b2 = last ? nB : cB + (size_t)(t + 2) * kstep;
;             const char* a3 = a2 + kstep; const char* b3 = b2 + kstep;
;             if (last && has_next) S.a_ready(nxt);
;             PG8_LDB(B0, 0, 0); PG8_SCHED; PG8_LDA(At, 0, 0); PG8_STAGE(PG8_SA(1, 1), a1 + hstep, voffA);
;             PG8_WAIT_L(8); PG8_BAR; PG8_WAIT_L(0); PG8_MMA(0, 0, At, B0); PG8_BAR; PG8_SCHED;
;             PG8_LDB(B1, 0, 1); PG8_STAGE(PG8_SB(0, 0), b2, voffB);
;             PG8_BAR; PG8_WAIT_L(0); PG8_MMA(0, 1, At, B1); PG8_BAR;
;             PG8_LDA(At, 0, 1); PG8_STAGE(PG8_SA(0, 0), a2, voffA);
;             PG8_BAR; PG8_WAIT_L(0); PG8_MMA(1, 0, At, B0); PG8_BAR; PG8_SCHED;
;             PG8_STAGE(PG8_SB(0, 1), b2 + hstep, voffB);
;             PG8_WAIT_V(6); PG8_BAR; PG8_MMA(1, 1, At, B1); PG8_BAR;
.LBB0_96:
	s_add_u32 s10, s8, 0x100
	s_addc_u32 s11, s9, 0
	s_add_i32 s46, 0, 0x10000
	v_add_u32_e32 v154, s46, v139
	ds_read_b128 v[142:145], v154
	ds_read_b128 v[146:149], v154 offset:1024
	ds_read_b128 v[150:153], v154 offset:2048
	ds_read_b128 v[154:157], v154 offset:3072
	s_cmp_eq_u32 s45, 40
	s_cselect_b32 s15, s1, s11
	s_cselect_b32 s14, s0, s10
	s_cselect_b32 s13, s5, s44
	s_cselect_b32 s12, s4, s43
	s_add_i32 m0, s20, 0xc000
	ds_read_b128 v[158:161], v141
	ds_read_b128 v[162:165], v141 offset:1024
	ds_read_b128 v[166:169], v141 offset:2048
	ds_read_b128 v[170:173], v141 offset:3072
	ds_read_b128 v[178:181], v141 offset:4096
	ds_read_b128 v[182:185], v141 offset:5120
	ds_read_b128 v[186:189], v141 offset:6144
	global_load_lds_dwordx4 v134, s[8:9]
	s_add_i32 m0, s20, 0xe000
	ds_read_b128 v[190:193], v141 offset:7168
	global_load_lds_dwordx4 v136, s[8:9]
	s_waitcnt lgkmcnt(8)
	s_barrier
	s_waitcnt lgkmcnt(0)
	s_setprio 1
	v_mfma_f32_16x16x32_bf16 v[124:127], v[142:145], v[158:161], v[124:127]
	v_mfma_f32_16x16x32_bf16 v[120:123], v[150:153], v[158:161], v[120:123]
	v_mfma_f32_16x16x32_bf16 v[116:119], v[142:145], v[166:169], v[116:119]
	v_mfma_f32_16x16x32_bf16 v[112:115], v[150:153], v[166:169], v[112:115]
	v_mfma_f32_16x16x32_bf16 v[100:103], v[142:145], v[178:181], v[100:103]
	v_mfma_f32_16x16x32_bf16 v[96:99], v[150:153], v[178:181], v[96:99]
	v_mfma_f32_16x16x32_bf16 v[84:87], v[142:145], v[186:189], v[84:87]
	v_mfma_f32_16x16x32_bf16 v[80:83], v[150:153], v[186:189], v[80:83]
	v_mfma_f32_16x16x32_bf16 v[124:127], v[146:149], v[162:165], v[124:127]
	v_mfma_f32_16x16x32_bf16 v[120:123], v[154:157], v[162:165], v[120:123]
	v_mfma_f32_16x16x32_bf16 v[116:119], v[146:149], v[170:173], v[116:119]
	v_mfma_f32_16x16x32_bf16 v[112:115], v[154:157], v[170:173], v[112:115]
	v_mfma_f32_16x16x32_bf16 v[100:103], v[146:149], v[182:185], v[100:103]
	v_mfma_f32_16x16x32_bf16 v[96:99], v[154:157], v[182:185], v[96:99]
	v_mfma_f32_16x16x32_bf16 v[84:87], v[146:149], v[190:193], v[84:87]
	v_mfma_f32_16x16x32_bf16 v[80:83], v[154:157], v[190:193], v[80:83]
	s_setprio 0
	s_barrier
	s_add_i32 s47, 0, 0x14000
	v_add_u32_e32 v174, s47, v139
	s_add_i32 s8, s46, s18
	ds_read_b128 v[194:197], v174
	ds_read_b128 v[198:201], v174 offset:1024
	ds_read_b128 v[202:205], v174 offset:2048
	s_add_u32 s98, s12, 0x80
	s_addc_u32 s99, s13, 0
	s_mov_b32 m0, s8
	ds_read_b128 v[206:209], v174 offset:3072
	global_load_lds_dwordx4 v176, s[12:13]
	s_add_i32 m0, s8, 0x2000
	s_nop 0
	global_load_lds_dwordx4 v128, s[12:13]
	s_barrier
	s_waitcnt lgkmcnt(0)
	s_setprio 1
	v_mfma_f32_16x16x32_bf16 v[108:111], v[194:197], v[158:161], v[108:111]
	v_mfma_f32_16x16x32_bf16 v[104:107], v[202:205], v[158:161], v[104:107]
	v_mfma_f32_16x16x32_bf16 v[92:95], v[194:197], v[166:169], v[92:95]
	v_mfma_f32_16x16x32_bf16 v[88:91], v[202:205], v[166:169], v[88:91]
	v_mfma_f32_16x16x32_bf16 v[76:79], v[194:197], v[178:181], v[76:79]
	v_mfma_f32_16x16x32_bf16 v[72:75], v[202:205], v[178:181], v[72:75]
	v_mfma_f32_16x16x32_bf16 v[68:71], v[194:197], v[186:189], v[68:71]
	v_mfma_f32_16x16x32_bf16 v[64:67], v[202:205], v[186:189], v[64:67]
	v_mfma_f32_16x16x32_bf16 v[108:111], v[198:201], v[162:165], v[108:111]
	v_mfma_f32_16x16x32_bf16 v[104:107], v[206:209], v[162:165], v[104:107]
	v_mfma_f32_16x16x32_bf16 v[92:95], v[198:201], v[170:173], v[92:95]
	v_mfma_f32_16x16x32_bf16 v[88:91], v[206:209], v[170:173], v[88:91]
	v_mfma_f32_16x16x32_bf16 v[76:79], v[198:201], v[182:185], v[76:79]
	v_mfma_f32_16x16x32_bf16 v[72:75], v[206:209], v[182:185], v[72:75]
	v_mfma_f32_16x16x32_bf16 v[68:71], v[198:201], v[190:193], v[68:71]
	v_mfma_f32_16x16x32_bf16 v[64:67], v[206:209], v[190:193], v[64:67]
	s_setprio 0
	s_mov_b32 m0, s20
	s_add_u32 s100, s14, 0x80
	s_addc_u32 s101, s15, 0
	s_barrier
	ds_read_b128 v[158:161], v141 offset:16384
	ds_read_b128 v[162:165], v141 offset:17408
	ds_read_b128 v[166:169], v141 offset:18432
	ds_read_b128 v[170:173], v141 offset:19456
	ds_read_b128 v[178:181], v141 offset:20480
	ds_read_b128 v[182:185], v141 offset:21504
	ds_read_b128 v[186:189], v141 offset:22528
	global_load_lds_dwordx4 v132, s[14:15]
	s_mov_b32 m0, s21
	ds_read_b128 v[190:193], v141 offset:23552
	global_load_lds_dwordx4 v130, s[14:15]
	s_barrier
	s_waitcnt lgkmcnt(0)
	s_setprio 1
	v_mfma_f32_16x16x32_bf16 v[60:63], v[142:145], v[158:161], v[60:63]
	v_mfma_f32_16x16x32_bf16 v[56:59], v[150:153], v[158:161], v[56:59]
	v_mfma_f32_16x16x32_bf16 v[52:55], v[142:145], v[166:169], v[52:55]
	v_mfma_f32_16x16x32_bf16 v[48:51], v[150:153], v[166:169], v[48:51]
	v_mfma_f32_16x16x32_bf16 v[36:39], v[142:145], v[178:181], v[36:39]
	v_mfma_f32_16x16x32_bf16 v[32:35], v[150:153], v[178:181], v[32:35]
	v_mfma_f32_16x16x32_bf16 v[20:23], v[142:145], v[186:189], v[20:23]
	v_mfma_f32_16x16x32_bf16 v[16:19], v[150:153], v[186:189], v[16:19]
	v_mfma_f32_16x16x32_bf16 v[60:63], v[146:149], v[162:165], v[60:63]
	v_mfma_f32_16x16x32_bf16 v[56:59], v[154:157], v[162:165], v[56:59]
	v_mfma_f32_16x16x32_bf16 v[52:55], v[146:149], v[170:173], v[52:55]
	v_mfma_f32_16x16x32_bf16 v[48:51], v[154:157], v[170:173], v[48:51]
	v_mfma_f32_16x16x32_bf16 v[36:39], v[146:149], v[182:185], v[36:39]
	v_mfma_f32_16x16x32_bf16 v[32:35], v[154:157], v[182:185], v[32:35]
	v_mfma_f32_16x16x32_bf16 v[20:23], v[146:149], v[190:193], v[20:23]
	v_mfma_f32_16x16x32_bf16 v[16:19], v[154:157], v[190:193], v[16:19]
	s_setprio 0
	s_barrier
	s_add_u32 s8, s12, 0xb0000
	s_addc_u32 s9, s13, 0
	s_add_i32 s46, s47, s18
	s_mov_b32 m0, s46
	s_nop 0
	global_load_lds_dwordx4 v176, s[8:9]
	s_add_i32 m0, s46, 0x2000
	s_nop 0
	global_load_lds_dwordx4 v128, s[8:9]
	s_waitcnt vmcnt(6)
	s_barrier
; #define PG8_STAGE(bufoff, gbase, voff) do { _Pragma("unroll") for (int _i = 0; _i < 2; ++_i) \
;         __builtin_amdgcn_global_load_lds((const unsigned*)((const char*)(gbase) + (voff)[_i]), (PG8_LAS unsigned*)(lds + (bufoff) + ldsw + _i * 8192), 16, 0, 0); } while (0)
; #define PG8_LDA(dst, b, h) do { _Pragma("unroll") for (int m = 0; m < 4; ++m) _Pragma("unroll") for (int k = 0; k < 2; ++k) dst[m][k] = *(const PG8_LAS bf16x8*)(lds + PG8_SA(b, h) + aoff + m * 2048 + k * 1024); } while (0)
; #define PG8_LDB(dst, b, h) do { _Pragma("unroll") for (int n = 0; n < 2; ++n) _Pragma("unroll") for (int k = 0; k < 2; ++k) dst[n][k] = *(const PG8_LAS bf16x8*)(lds + PG8_SB(b, h) + boff + n * 2048 + k * 1024); } while (0)
; #define PG8_MMA(ai, bj, At, Bt) do { __builtin_amdgcn_s_setprio(1); _Pragma("unroll") for (int m = 0; m < 4; ++m) _Pragma("unroll") for (int n = 0; n < 2; ++n) _Pragma("unroll") for (int k = 0; k < 2; ++k) \
;         acc[ai][bj][m][n] = __builtin_amdgcn_mfma_f32_16x16x32_bf16(Bt[n][k], At[m][k], acc[ai][bj][m][n], 0, 0, 0); __builtin_amdgcn_s_setprio(0); } while (0)
; #define PG8_WAIT_V(n) asm volatile("s_waitcnt vmcnt(" #n ")" ::: "memory")
; #define PG8_WAIT_L(n) asm volatile("s_waitcnt lgkmcnt(" #n ")" ::: "memory")
; #define PG8_BAR __builtin_amdgcn_s_barrier()
; #define PG8_SCHED __builtin_amdgcn_sched_barrier(0)
; template <class Epi, class Sched>
; __device__ __forceinline__ void gemm_phase(PG8_LAS unsigned char* lds, const Gemm g, const Sched& S, const Epi& E) {
;     ...
;             PG8_WAIT_V(6); PG8_BAR; PG8_MMA(1, 1, At, B1); PG8_BAR;
;             PG8_LDB(B0, 1, 0); PG8_SCHED; PG8_LDA(At, 1, 0); PG8_STAGE(PG8_SA(0, 1), a2 + hstep, voffA);
;             PG8_WAIT_L(8); PG8_BAR; PG8_WAIT_L(0); PG8_MMA(0, 0, At, B0); PG8_BAR; PG8_SCHED;
;             PG8_LDB(B1, 1, 1); PG8_STAGE(PG8_SB(1, 0), b3, voffB);
;             PG8_BAR; PG8_WAIT_L(0); PG8_MMA(0, 1, At, B1); PG8_BAR;
;             PG8_LDA(At, 1, 1); PG8_STAGE(PG8_SA(1, 0), a3, voffA);
;             PG8_BAR; PG8_WAIT_L(0); PG8_MMA(1, 0, At, B0); PG8_BAR; PG8_SCHED;
	s_setprio 1
	v_mfma_f32_16x16x32_bf16 v[44:47], v[194:197], v[158:161], v[44:47]
	v_mfma_f32_16x16x32_bf16 v[40:43], v[202:205], v[158:161], v[40:43]
	v_mfma_f32_16x16x32_bf16 v[28:31], v[194:197], v[166:169], v[28:31]
	v_mfma_f32_16x16x32_bf16 v[24:27], v[202:205], v[166:169], v[24:27]
	v_mfma_f32_16x16x32_bf16 v[12:15], v[194:197], v[178:181], v[12:15]
	v_mfma_f32_16x16x32_bf16 v[8:11], v[202:205], v[178:181], v[8:11]
	v_mfma_f32_16x16x32_bf16 v[4:7], v[194:197], v[186:189], v[4:7]
	v_mfma_f32_16x16x32_bf16 v[0:3], v[202:205], v[186:189], v[0:3]
	v_mfma_f32_16x16x32_bf16 v[44:47], v[198:201], v[162:165], v[44:47]
	v_mfma_f32_16x16x32_bf16 v[40:43], v[206:209], v[162:165], v[40:43]
	v_mfma_f32_16x16x32_bf16 v[28:31], v[198:201], v[170:173], v[28:31]
	v_mfma_f32_16x16x32_bf16 v[24:27], v[206:209], v[170:173], v[24:27]
	v_mfma_f32_16x16x32_bf16 v[12:15], v[198:201], v[182:185], v[12:15]
	v_mfma_f32_16x16x32_bf16 v[8:11], v[206:209], v[182:185], v[8:11]
	v_mfma_f32_16x16x32_bf16 v[4:7], v[198:201], v[190:193], v[4:7]
	v_mfma_f32_16x16x32_bf16 v[0:3], v[206:209], v[190:193], v[0:3]
	s_setprio 0
	s_add_i32 s46, 0, 0x18000
	v_add_u32_e32 v154, s46, v139
	s_barrier
	ds_read_b128 v[142:145], v154
	ds_read_b128 v[146:149], v154 offset:1024
	ds_read_b128 v[150:153], v154 offset:2048
	ds_read_b128 v[154:157], v154 offset:3072
	s_add_u32 s8, s14, 0xb0000
	s_addc_u32 s9, s15, 0
	s_mov_b32 m0, s22
	ds_read_b128 v[158:161], v141 offset:32768
	ds_read_b128 v[162:165], v141 offset:33792
	ds_read_b128 v[166:169], v141 offset:34816
	ds_read_b128 v[170:173], v141 offset:35840
	ds_read_b128 v[178:181], v141 offset:36864
	ds_read_b128 v[182:185], v141 offset:37888
	ds_read_b128 v[186:189], v141 offset:38912
	global_load_lds_dwordx4 v132, s[8:9]
	s_mov_b32 m0, s23
	ds_read_b128 v[190:193], v141 offset:39936
	global_load_lds_dwordx4 v130, s[8:9]
	s_waitcnt lgkmcnt(8)
	s_barrier
	s_waitcnt lgkmcnt(0)
	s_setprio 1
	v_mfma_f32_16x16x32_bf16 v[124:127], v[142:145], v[158:161], v[124:127]
	v_mfma_f32_16x16x32_bf16 v[120:123], v[150:153], v[158:161], v[120:123]
	v_mfma_f32_16x16x32_bf16 v[116:119], v[142:145], v[166:169], v[116:119]
	v_mfma_f32_16x16x32_bf16 v[112:115], v[150:153], v[166:169], v[112:115]
	v_mfma_f32_16x16x32_bf16 v[100:103], v[142:145], v[178:181], v[100:103]
	v_mfma_f32_16x16x32_bf16 v[96:99], v[150:153], v[178:181], v[96:99]
	v_mfma_f32_16x16x32_bf16 v[84:87], v[142:145], v[186:189], v[84:87]
	v_mfma_f32_16x16x32_bf16 v[80:83], v[150:153], v[186:189], v[80:83]
	v_mfma_f32_16x16x32_bf16 v[124:127], v[146:149], v[162:165], v[124:127]
	v_mfma_f32_16x16x32_bf16 v[120:123], v[154:157], v[162:165], v[120:123]
	v_mfma_f32_16x16x32_bf16 v[116:119], v[146:149], v[170:173], v[116:119]
	v_mfma_f32_16x16x32_bf16 v[112:115], v[154:157], v[170:173], v[112:115]
	v_mfma_f32_16x16x32_bf16 v[100:103], v[146:149], v[182:185], v[100:103]
	v_mfma_f32_16x16x32_bf16 v[96:99], v[154:157], v[182:185], v[96:99]
	v_mfma_f32_16x16x32_bf16 v[84:87], v[146:149], v[190:193], v[84:87]
	v_mfma_f32_16x16x32_bf16 v[80:83], v[154:157], v[190:193], v[80:83]
	s_setprio 0
	s_barrier
	s_add_i32 s14, 0, 0x1c000
	s_add_i32 s8, s46, s18
	v_add_u32_e32 v206, s14, v139
	s_mov_b32 m0, s8
	ds_read_b128 v[194:197], v206
	ds_read_b128 v[198:201], v206 offset:1024
	ds_read_b128 v[202:205], v206 offset:2048
	global_load_lds_dwordx4 v176, s[98:99]
	s_add_i32 m0, s8, 0x2000
	ds_read_b128 v[206:209], v206 offset:3072
	global_load_lds_dwordx4 v128, s[98:99]
	s_barrier
	s_waitcnt lgkmcnt(0)
	s_setprio 1
	v_mfma_f32_16x16x32_bf16 v[108:111], v[194:197], v[158:161], v[108:111]
	v_mfma_f32_16x16x32_bf16 v[104:107], v[202:205], v[158:161], v[104:107]
	v_mfma_f32_16x16x32_bf16 v[92:95], v[194:197], v[166:169], v[92:95]
	v_mfma_f32_16x16x32_bf16 v[88:91], v[202:205], v[166:169], v[88:91]
	v_mfma_f32_16x16x32_bf16 v[76:79], v[194:197], v[178:181], v[76:79]
	v_mfma_f32_16x16x32_bf16 v[72:75], v[202:205], v[178:181], v[72:75]
	v_mfma_f32_16x16x32_bf16 v[68:71], v[194:197], v[186:189], v[68:71]
	v_mfma_f32_16x16x32_bf16 v[64:67], v[202:205], v[186:189], v[64:67]
	v_mfma_f32_16x16x32_bf16 v[108:111], v[198:201], v[162:165], v[108:111]
	v_mfma_f32_16x16x32_bf16 v[104:107], v[206:209], v[162:165], v[104:107]
	v_mfma_f32_16x16x32_bf16 v[92:95], v[198:201], v[170:173], v[92:95]
	v_mfma_f32_16x16x32_bf16 v[88:91], v[206:209], v[170:173], v[88:91]
	v_mfma_f32_16x16x32_bf16 v[76:79], v[198:201], v[182:185], v[76:79]
	v_mfma_f32_16x16x32_bf16 v[72:75], v[206:209], v[182:185], v[72:75]
	v_mfma_f32_16x16x32_bf16 v[68:71], v[198:201], v[190:193], v[68:71]
	v_mfma_f32_16x16x32_bf16 v[64:67], v[206:209], v[190:193], v[64:67]
	s_setprio 0
	s_mov_b32 m0, s27
	s_barrier
	ds_read_b128 v[158:161], v141 offset:49152
	ds_read_b128 v[162:165], v141 offset:50176
	ds_read_b128 v[166:169], v141 offset:51200
	ds_read_b128 v[170:173], v141 offset:52224
	ds_read_b128 v[178:181], v141 offset:53248
	ds_read_b128 v[182:185], v141 offset:54272
	ds_read_b128 v[186:189], v141 offset:55296
	global_load_lds_dwordx4 v132, s[100:101]
	s_mov_b32 m0, s28
	ds_read_b128 v[190:193], v141 offset:56320
	global_load_lds_dwordx4 v130, s[100:101]
	s_barrier
; #define PG8_STAGE(bufoff, gbase, voff) do { _Pragma("unroll") for (int _i = 0; _i < 2; ++_i) \
;         __builtin_amdgcn_global_load_lds((const unsigned*)((const char*)(gbase) + (voff)[_i]), (PG8_LAS unsigned*)(lds + (bufoff) + ldsw + _i * 8192), 16, 0, 0); } while (0)
; #define PG8_MMA(ai, bj, At, Bt) do { __builtin_amdgcn_s_setprio(1); _Pragma("unroll") for (int m = 0; m < 4; ++m) _Pragma("unroll") for (int n = 0; n < 2; ++n) _Pragma("unroll") for (int k = 0; k < 2; ++k) \
;         acc[ai][bj][m][n] = __builtin_amdgcn_mfma_f32_16x16x32_bf16(Bt[n][k], At[m][k], acc[ai][bj][m][n], 0, 0, 0); __builtin_amdgcn_s_setprio(0); } while (0)
; #define PG8_WAIT_V(n) asm volatile("s_waitcnt vmcnt(" #n ")" ::: "memory")
; #define PG8_WAIT_L(n) asm volatile("s_waitcnt lgkmcnt(" #n ")" ::: "memory")
; #define PG8_BAR __builtin_amdgcn_s_barrier()
; #define PG8_SCHED __builtin_amdgcn_sched_barrier(0)
; template <class Epi, class Sched>
; __device__ __forceinline__ void gemm_phase(PG8_LAS unsigned char* lds, const Gemm g, const Sched& S, const Epi& E) {
;     ...
;             PG8_BAR; PG8_WAIT_L(0); PG8_MMA(1, 0, At, B0); PG8_BAR; PG8_SCHED;
;             PG8_STAGE(PG8_SB(1, 1), b3 + hstep, voffB);
;             PG8_WAIT_V(6); PG8_BAR; PG8_MMA(1, 1, At, B1); PG8_BAR;
;         }
	s_waitcnt lgkmcnt(0)
	s_setprio 1
	v_mfma_f32_16x16x32_bf16 v[60:63], v[142:145], v[158:161], v[60:63]
	v_mfma_f32_16x16x32_bf16 v[56:59], v[150:153], v[158:161], v[56:59]
	v_mfma_f32_16x16x32_bf16 v[52:55], v[142:145], v[166:169], v[52:55]
	v_mfma_f32_16x16x32_bf16 v[48:51], v[150:153], v[166:169], v[48:51]
	v_mfma_f32_16x16x32_bf16 v[36:39], v[142:145], v[178:181], v[36:39]
	v_mfma_f32_16x16x32_bf16 v[32:35], v[150:153], v[178:181], v[32:35]
	v_mfma_f32_16x16x32_bf16 v[20:23], v[142:145], v[186:189], v[20:23]
	v_mfma_f32_16x16x32_bf16 v[16:19], v[150:153], v[186:189], v[16:19]
	v_mfma_f32_16x16x32_bf16 v[60:63], v[146:149], v[162:165], v[60:63]
	v_mfma_f32_16x16x32_bf16 v[56:59], v[154:157], v[162:165], v[56:59]
	v_mfma_f32_16x16x32_bf16 v[52:55], v[146:149], v[170:173], v[52:55]
	v_mfma_f32_16x16x32_bf16 v[48:51], v[154:157], v[170:173], v[48:51]
	v_mfma_f32_16x16x32_bf16 v[36:39], v[146:149], v[182:185], v[36:39]
	v_mfma_f32_16x16x32_bf16 v[32:35], v[154:157], v[182:185], v[32:35]
	v_mfma_f32_16x16x32_bf16 v[20:23], v[146:149], v[190:193], v[20:23]
	v_mfma_f32_16x16x32_bf16 v[16:19], v[154:157], v[190:193], v[16:19]
	s_setprio 0
	s_barrier
	s_add_u32 s8, s12, 0xb0080
	s_addc_u32 s9, s13, 0
	s_add_i32 s12, s14, s18
	s_mov_b32 m0, s12
	s_nop 0
	global_load_lds_dwordx4 v176, s[8:9]
	s_add_i32 m0, s12, 0x2000
	s_nop 0
	global_load_lds_dwordx4 v128, s[8:9]
	s_waitcnt vmcnt(6)
	s_barrier
	s_setprio 1
	v_mfma_f32_16x16x32_bf16 v[44:47], v[194:197], v[158:161], v[44:47]
	v_mfma_f32_16x16x32_bf16 v[40:43], v[202:205], v[158:161], v[40:43]
	v_mfma_f32_16x16x32_bf16 v[28:31], v[194:197], v[166:169], v[28:31]
	v_mfma_f32_16x16x32_bf16 v[24:27], v[202:205], v[166:169], v[24:27]
	v_mfma_f32_16x16x32_bf16 v[12:15], v[194:197], v[178:181], v[12:15]
	v_mfma_f32_16x16x32_bf16 v[8:11], v[202:205], v[178:181], v[8:11]
	v_mfma_f32_16x16x32_bf16 v[4:7], v[194:197], v[186:189], v[4:7]
	v_mfma_f32_16x16x32_bf16 v[0:3], v[202:205], v[186:189], v[0:3]
	v_mfma_f32_16x16x32_bf16 v[44:47], v[198:201], v[162:165], v[44:47]
	v_mfma_f32_16x16x32_bf16 v[40:43], v[206:209], v[162:165], v[40:43]
	v_mfma_f32_16x16x32_bf16 v[28:31], v[198:201], v[170:173], v[28:31]
	v_mfma_f32_16x16x32_bf16 v[24:27], v[206:209], v[170:173], v[24:27]
	v_mfma_f32_16x16x32_bf16 v[12:15], v[198:201], v[182:185], v[12:15]
	v_mfma_f32_16x16x32_bf16 v[8:11], v[206:209], v[182:185], v[8:11]
	v_mfma_f32_16x16x32_bf16 v[4:7], v[198:201], v[190:193], v[4:7]
	v_mfma_f32_16x16x32_bf16 v[0:3], v[206:209], v[190:193], v[0:3]
	s_setprio 0
	s_add_i32 s45, s45, 2
	s_add_u32 s43, s43, 0x100
	s_addc_u32 s44, s44, 0
	s_cmp_gt_u32 s45, 41
	s_mov_b64 s[8:9], s[10:11]
	s_barrier
	s_cbranch_scc0 .LBB0_96
; __device__ __forceinline__ unsigned cvtpk(float lo, float hi) { const f32x2 v = (f32x2){lo, hi}; const bf16v2 b = __builtin_convertvector(v, bf16v2); return __builtin_bit_cast(unsigned, b); }
; #define PG8_WAIT_V(n) asm volatile("s_waitcnt vmcnt(" #n ")" ::: "memory")
; #define PG8_BAR __builtin_amdgcn_s_barrier()
; template <class Epi, class Sched>
; __device__ __forceinline__ void gemm_phase(PG8_LAS unsigned char* lds, const Gemm g, const Sched& S, const Epi& E) {
;     ...
;         if constexpr (!Epi::AFTER_DRAIN) { E(acc, cur, wr, wc, fr, fq); S.done(cur); }
;         if (!has_next) break;
; #pragma unroll
;         for (int a = 0; a < 2; ++a)
; #pragma unroll
;             for (int b = 0; b < 2; ++b)
; #pragma unroll
;                 for (int m = 0; m < 4; ++m)
; #pragma unroll
;                     for (int n = 0; n < 2; ++n) acc[a][b][m][n] = (f32x4){0.f, 0.f, 0.f, 0.f};
;         cur = nxt; cA = nA; cB = nB; ++ui;
;     }
;     PG8_WAIT_V(0);
;     if (wr == 0) PG8_BAR;
;     __device__ __forceinline__ void operator()(const f32x4 (&acc)[2][2][4][2], const pg8::Unit& u, int wr, int wc, int fr, int fq) const {
;         const int row0 = u.pm * 256 + wr * 64 + fr, col0 = u.pn * 256 + wc * 32 + 8 * fq;
; #pragma unroll
;         for (int ai = 0; ai < 2; ++ai)
; #pragma unroll
;             for (int m = 0; m < 4; ++m) { bf16_t* rowp = O + (size_t)(row0 + ai * 128 + m * 16) * ldc + col0;
; #pragma unroll
;                 for (int bj = 0; bj < 2; ++bj) { const f32x4 v0 = acc[ai][bj][m][0], v1 = acc[ai][bj][m][1];
;                     u32x4 w; w.x = cvtpk(v0[0], v0[1]); w.y = cvtpk(v0[2], v0[3]); w.z = cvtpk(v1[0], v1[1]); w.w = cvtpk(v1[2], v1[3]);
;                     *(u32x4*)(rowp + bj * 128) = w; } }
	v_lshl_add_u32 v142, s29, 8, v138
	v_lshl_or_b32 v144, s34, 8, v140
	v_ashrrev_i32_e32 v143, 31, v142
	v_readlane_b32 s8, v253, 18
	v_cvt_pk_bf16_f32 v108, v108, v109
	v_cvt_pk_bf16_f32 v109, v110, v111
	v_cvt_pk_bf16_f32 v110, v104, v105
	v_or_b32_e32 v104, 16, v142
	v_cvt_pk_bf16_f32 v92, v92, v93
	v_cvt_pk_bf16_f32 v93, v94, v95
	v_cvt_pk_bf16_f32 v94, v88, v89
	v_or_b32_e32 v88, 32, v142
	v_cvt_pk_bf16_f32 v76, v76, v77
	v_cvt_pk_bf16_f32 v77, v78, v79
	v_cvt_pk_bf16_f32 v78, v72, v73
	v_or_b32_e32 v72, 48, v142
	v_ashrrev_i32_e32 v145, 31, v144
	v_lshlrev_b64 v[146:147], 11, v[142:143]
	v_readlane_b32 s9, v253, 19
	v_ashrrev_i32_e32 v105, 31, v104
	v_ashrrev_i32_e32 v89, 31, v88
	v_ashrrev_i32_e32 v73, 31, v72
	v_lshl_add_u64 v[146:147], s[8:9], 0, v[146:147]
	v_lshlrev_b64 v[144:145], 1, v[144:145]
	v_lshlrev_b64 v[104:105], 11, v[104:105]
	v_lshlrev_b64 v[88:89], 11, v[88:89]
	v_lshlrev_b64 v[72:73], 11, v[72:73]
	v_lshl_add_u64 v[146:147], v[146:147], 0, v[144:145]
	v_lshl_add_u64 v[104:105], s[8:9], 0, v[104:105]
	v_lshl_add_u64 v[88:89], s[8:9], 0, v[88:89]
	v_lshl_add_u64 v[72:73], s[8:9], 0, v[72:73]
	s_mov_b64 s[8:9], 0x40000
	v_cvt_pk_bf16_f32 v68, v68, v69
	v_cvt_pk_bf16_f32 v69, v70, v71
	v_cvt_pk_bf16_f32 v70, v64, v65
	v_lshl_add_u64 v[64:65], v[146:147], 0, s[8:9]
	v_cvt_pk_bf16_f32 v60, v60, v61
	v_cvt_pk_bf16_f32 v61, v62, v63
	v_cvt_pk_bf16_f32 v62, v56, v57
	v_add_co_u32_e32 v56, vcc, s2, v146
	v_cvt_pk_bf16_f32 v44, v44, v45
	v_cvt_pk_bf16_f32 v45, v46, v47
	v_cvt_pk_bf16_f32 v46, v40, v41
	v_cvt_pk_bf16_f32 v47, v42, v43
	s_mov_b64 s[8:9], 0x48000
	v_addc_co_u32_e32 v57, vcc, 0, v147, vcc
	global_store_dwordx4 v[64:65], v[44:47], off offset:256
	v_cvt_pk_bf16_f32 v28, v28, v29
	v_cvt_pk_bf16_f32 v29, v30, v31
	v_lshl_add_u64 v[44:45], v[146:147], 0, s[8:9]
	s_mov_b32 s8, 0x48000
	v_add_co_u32_e32 v46, vcc, s8, v146
	v_cvt_pk_bf16_f32 v30, v24, v25
	v_cvt_pk_bf16_f32 v31, v26, v27
	s_mov_b64 s[8:9], 0x50000
	v_addc_co_u32_e32 v47, vcc, 0, v147, vcc
	global_store_dwordx4 v[44:45], v[28:31], off offset:256
	v_cvt_pk_bf16_f32 v12, v12, v13
	v_cvt_pk_bf16_f32 v13, v14, v15
	v_lshl_add_u64 v[28:29], v[146:147], 0, s[8:9]
	s_mov_b32 s8, 0x50000
	v_add_co_u32_e32 v30, vcc, s8, v146
	v_cvt_pk_bf16_f32 v14, v8, v9
	v_cvt_pk_bf16_f32 v15, v10, v11
	s_mov_b64 s[8:9], 0x58000
	v_cvt_pk_bf16_f32 v111, v106, v107
	v_addc_co_u32_e32 v31, vcc, 0, v147, vcc
	global_store_dwordx4 v[28:29], v[12:15], off offset:256
	global_store_dwordx4 v[146:147], v[108:111], off offset:256
	v_cvt_pk_bf16_f32 v95, v90, v91
	v_lshl_add_u64 v[12:13], v[146:147], 0, s[8:9]
	s_mov_b32 s8, 0x58000
	v_lshl_add_u64 v[108:109], v[104:105], 0, v[144:145]
	v_add_co_u32_e32 v14, vcc, s8, v146
	global_store_dwordx4 v[108:109], v[92:95], off offset:256
	v_cvt_pk_bf16_f32 v79, v74, v75
	v_addc_co_u32_e32 v15, vcc, 0, v147, vcc
	v_lshl_add_u64 v[92:93], v[88:89], 0, v[144:145]
	v_cvt_pk_bf16_f32 v124, v124, v125
	v_cvt_pk_bf16_f32 v125, v126, v127
	v_cvt_pk_bf16_f32 v126, v120, v121
	v_cvt_pk_bf16_f32 v127, v122, v123
	v_cvt_pk_bf16_f32 v104, v116, v117
	v_cvt_pk_bf16_f32 v105, v118, v119
	v_cvt_pk_bf16_f32 v106, v112, v113
	v_cvt_pk_bf16_f32 v107, v114, v115
	v_cvt_pk_bf16_f32 v88, v100, v101
	v_cvt_pk_bf16_f32 v89, v102, v103
	v_cvt_pk_bf16_f32 v90, v96, v97
	v_cvt_pk_bf16_f32 v91, v98, v99
	global_store_dwordx4 v[92:93], v[76:79], off offset:256
	v_cvt_pk_bf16_f32 v74, v80, v81
	v_cvt_pk_bf16_f32 v75, v82, v83
	v_lshl_add_u64 v[76:77], v[72:73], 0, v[144:145]
	v_cvt_pk_bf16_f32 v72, v84, v85
	v_cvt_pk_bf16_f32 v73, v86, v87
	v_cvt_pk_bf16_f32 v71, v66, v67
	v_cvt_pk_bf16_f32 v63, v58, v59
	v_cvt_pk_bf16_f32 v40, v52, v53
	v_cvt_pk_bf16_f32 v41, v54, v55
	v_cvt_pk_bf16_f32 v42, v48, v49
	v_cvt_pk_bf16_f32 v43, v50, v51
	v_cvt_pk_bf16_f32 v24, v36, v37
	v_cvt_pk_bf16_f32 v25, v38, v39
	v_cvt_pk_bf16_f32 v26, v32, v33
	v_cvt_pk_bf16_f32 v27, v34, v35
	v_cvt_pk_bf16_f32 v8, v20, v21
	v_cvt_pk_bf16_f32 v9, v22, v23
	v_cvt_pk_bf16_f32 v10, v16, v17
	v_cvt_pk_bf16_f32 v11, v18, v19
	v_cvt_pk_bf16_f32 v4, v4, v5
	v_cvt_pk_bf16_f32 v5, v6, v7
	v_cvt_pk_bf16_f32 v6, v0, v1
	v_cvt_pk_bf16_f32 v7, v2, v3
	s_and_b64 vcc, exec, s[38:39]
	s_mov_b32 s34, s40
	s_mov_b32 s29, s41
	s_mov_b64 s[10:11], s[4:5]
	s_mov_b64 s[8:9], s[0:1]
	global_store_dwordx4 v[146:147], v[124:127], off
	global_store_dwordx4 v[108:109], v[104:107], off
	global_store_dwordx4 v[92:93], v[88:91], off
	global_store_dwordx4 v[76:77], v[72:75], off
	global_store_dwordx4 v[76:77], v[68:71], off offset:256
	global_store_dwordx4 v[56:57], v[60:63], off
	global_store_dwordx4 v[46:47], v[40:43], off
	global_store_dwordx4 v[30:31], v[24:27], off
	global_store_dwordx4 v[14:15], v[8:11], off
	global_store_dwordx4 v[12:13], v[4:7], off offset:256
	s_cbranch_vccz .LBB0_89
	s_waitcnt vmcnt(0)
	s_cmpk_gt_u32 s17, 0xff
	v_readlane_b32 s2, v254, 59
	s_cbranch_scc1 .LBB0_100
	s_barrier

; #define PG8_STAGE(bufoff, gbase, voff) do { _Pragma("unroll") for (int _i = 0; _i < 2; ++_i) \
;         __builtin_amdgcn_global_load_lds((const unsigned*)((const char*)(gbase) + (voff)[_i]), (PG8_LAS unsigned*)(lds + (bufoff) + ldsw + _i * 8192), 16, 0, 0); } while (0)
; #define PG8_LDA(dst, b, h) do { _Pragma("unroll") for (int m = 0; m < 4; ++m) _Pragma("unroll") for (int k = 0; k < 2; ++k) dst[m][k] = *(const PG8_LAS bf16x8*)(lds + PG8_SA(b, h) + aoff + m * 2048 + k * 1024); } while (0)
; #define PG8_LDB(dst, b, h) do { _Pragma("unroll") for (int n = 0; n < 2; ++n) _Pragma("unroll") for (int k = 0; k < 2; ++k) dst[n][k] = *(const PG8_LAS bf16x8*)(lds + PG8_SB(b, h) + boff + n * 2048 + k * 1024); } while (0)
; #define PG8_MMA(ai, bj, At, Bt) do { __builtin_amdgcn_s_setprio(1); _Pragma("unroll") for (int m = 0; m < 4; ++m) _Pragma("unroll") for (int n = 0; n < 2; ++n) _Pragma("unroll") for (int k = 0; k < 2; ++k) \
;         acc[ai][bj][m][n] = __builtin_amdgcn_mfma_f32_16x16x32_bf16(Bt[n][k], At[m][k], acc[ai][bj][m][n], 0, 0, 0); __builtin_amdgcn_s_setprio(0); } while (0)
; #define PG8_WAIT_V(n) asm volatile("s_waitcnt vmcnt(" #n ")" ::: "memory")
; template <class Epi, class Sched>
; __device__ __forceinline__ void gemm_phase(PG8_LAS unsigned char* lds, const Gemm g, const Sched& S, const Epi& E) {
;     ...
;         for (int t = 0; t < nt; t += 2) {
;             const bool last = (t == nt - 2);
;             const char* a1 = cA + (size_t)(t + 1) * kstep;
;             const char* a2 = last ? nA : cA + (size_t)(t + 2) * kstep; const char* b2 = last ? nB : cB + (size_t)(t + 2) * kstep;
;             const char* a3 = a2 + kstep; const char* b3 = b2 + kstep;
;             if (last && has_next) S.a_ready(nxt);
;             PG8_LDB(B0, 0, 0); PG8_SCHED; PG8_LDA(At, 0, 0); PG8_STAGE(PG8_SA(1, 1), a1 + hstep, voffA);
;             PG8_WAIT_L(8); PG8_BAR; PG8_WAIT_L(0); PG8_MMA(0, 0, At, B0); PG8_BAR; PG8_SCHED;
;             PG8_LDB(B1, 0, 1); PG8_STAGE(PG8_SB(0, 0), b2, voffB);
;             PG8_BAR; PG8_WAIT_L(0); PG8_MMA(0, 1, At, B1); PG8_BAR;
;             PG8_LDA(At, 0, 1); PG8_STAGE(PG8_SA(0, 0), a2, voffA);
;             PG8_BAR; PG8_WAIT_L(0); PG8_MMA(1, 0, At, B0); PG8_BAR; PG8_SCHED;
;             PG8_STAGE(PG8_SB(0, 1), b2 + hstep, voffB);
;             PG8_WAIT_V(6); PG8_BAR; PG8_MMA(1, 1, At, B1); PG8_BAR;
.LBB0_114:
	s_add_u32 s14, s12, 0xfffc0080
	s_addc_u32 s15, s13, -1
	s_add_i32 s46, 0, 0x10000
	v_add_u32_e32 v154, s46, v143
	ds_read_b128 v[138:141], v154
	ds_read_b128 v[146:149], v154 offset:1024
	ds_read_b128 v[150:153], v154 offset:2048
	ds_read_b128 v[154:157], v154 offset:3072
	s_cmp_eq_u32 s45, 12
	s_cselect_b32 s17, s5, s15
	s_cselect_b32 s16, s40, s14
	s_cselect_b32 s15, s1, s44
	s_cselect_b32 s14, s41, s43
	s_add_i32 m0, s11, 0xc000
	ds_read_b128 v[158:161], v145
	ds_read_b128 v[162:165], v145 offset:1024
	ds_read_b128 v[166:169], v145 offset:2048
	ds_read_b128 v[170:173], v145 offset:3072
	ds_read_b128 v[178:181], v145 offset:4096
	ds_read_b128 v[182:185], v145 offset:5120
	ds_read_b128 v[186:189], v145 offset:6144
	global_load_lds_dwordx4 v134, s[12:13]
	s_add_i32 m0, s11, 0xe000
	ds_read_b128 v[190:193], v145 offset:7168
	global_load_lds_dwordx4 v136, s[12:13]
	s_waitcnt lgkmcnt(8)
	s_barrier
	s_waitcnt lgkmcnt(0)
	s_setprio 1
	v_mfma_f32_16x16x32_bf16 v[124:127], v[138:141], v[158:161], v[124:127]
	v_mfma_f32_16x16x32_bf16 v[116:119], v[150:153], v[158:161], v[116:119]
	v_mfma_f32_16x16x32_bf16 v[108:111], v[138:141], v[166:169], v[108:111]
	v_mfma_f32_16x16x32_bf16 v[100:103], v[150:153], v[166:169], v[100:103]
	v_mfma_f32_16x16x32_bf16 v[92:95], v[138:141], v[178:181], v[92:95]
	v_mfma_f32_16x16x32_bf16 v[84:87], v[150:153], v[178:181], v[84:87]
	v_mfma_f32_16x16x32_bf16 v[76:79], v[138:141], v[186:189], v[76:79]
	v_mfma_f32_16x16x32_bf16 v[68:71], v[150:153], v[186:189], v[68:71]
	v_mfma_f32_16x16x32_bf16 v[124:127], v[146:149], v[162:165], v[124:127]
	v_mfma_f32_16x16x32_bf16 v[116:119], v[154:157], v[162:165], v[116:119]
	v_mfma_f32_16x16x32_bf16 v[108:111], v[146:149], v[170:173], v[108:111]
	v_mfma_f32_16x16x32_bf16 v[100:103], v[154:157], v[170:173], v[100:103]
	v_mfma_f32_16x16x32_bf16 v[92:95], v[146:149], v[182:185], v[92:95]
	v_mfma_f32_16x16x32_bf16 v[84:87], v[154:157], v[182:185], v[84:87]
	v_mfma_f32_16x16x32_bf16 v[76:79], v[146:149], v[190:193], v[76:79]
	v_mfma_f32_16x16x32_bf16 v[68:71], v[154:157], v[190:193], v[68:71]
	s_setprio 0
	s_barrier
	s_add_i32 s48, 0, 0x14000
	v_add_u32_e32 v174, s48, v143
	s_add_i32 s46, s46, s20
	ds_read_b128 v[194:197], v174
	ds_read_b128 v[198:201], v174 offset:1024
	ds_read_b128 v[202:205], v174 offset:2048
	s_add_u32 s98, s14, 0x80
	s_addc_u32 s99, s15, 0
	s_mov_b32 m0, s46
	ds_read_b128 v[206:209], v174 offset:3072
	global_load_lds_dwordx4 v176, s[14:15]
	s_add_i32 m0, s46, 0x2000
	s_nop 0
	global_load_lds_dwordx4 v128, s[14:15]
	s_barrier
	s_waitcnt lgkmcnt(0)
	s_setprio 1
	v_mfma_f32_16x16x32_bf16 v[120:123], v[194:197], v[158:161], v[120:123]
	v_mfma_f32_16x16x32_bf16 v[112:115], v[202:205], v[158:161], v[112:115]
	v_mfma_f32_16x16x32_bf16 v[104:107], v[194:197], v[166:169], v[104:107]
	v_mfma_f32_16x16x32_bf16 v[96:99], v[202:205], v[166:169], v[96:99]
	v_mfma_f32_16x16x32_bf16 v[88:91], v[194:197], v[178:181], v[88:91]
	v_mfma_f32_16x16x32_bf16 v[80:83], v[202:205], v[178:181], v[80:83]
	v_mfma_f32_16x16x32_bf16 v[72:75], v[194:197], v[186:189], v[72:75]
	v_mfma_f32_16x16x32_bf16 v[64:67], v[202:205], v[186:189], v[64:67]
	v_mfma_f32_16x16x32_bf16 v[120:123], v[198:201], v[162:165], v[120:123]
	v_mfma_f32_16x16x32_bf16 v[112:115], v[206:209], v[162:165], v[112:115]
	v_mfma_f32_16x16x32_bf16 v[104:107], v[198:201], v[170:173], v[104:107]
	v_mfma_f32_16x16x32_bf16 v[96:99], v[206:209], v[170:173], v[96:99]
	v_mfma_f32_16x16x32_bf16 v[88:91], v[198:201], v[182:185], v[88:91]
	v_mfma_f32_16x16x32_bf16 v[80:83], v[206:209], v[182:185], v[80:83]
	v_mfma_f32_16x16x32_bf16 v[72:75], v[198:201], v[190:193], v[72:75]
	v_mfma_f32_16x16x32_bf16 v[64:67], v[206:209], v[190:193], v[64:67]
	s_setprio 0
	s_mov_b32 m0, s11
	s_add_u32 s100, s16, 0x80
	s_addc_u32 s101, s17, 0
	s_barrier
	ds_read_b128 v[158:161], v145 offset:16384
	ds_read_b128 v[162:165], v145 offset:17408
	ds_read_b128 v[166:169], v145 offset:18432
	ds_read_b128 v[170:173], v145 offset:19456
	ds_read_b128 v[178:181], v145 offset:20480
	ds_read_b128 v[182:185], v145 offset:21504
	ds_read_b128 v[186:189], v145 offset:22528
	global_load_lds_dwordx4 v132, s[16:17]
	s_mov_b32 m0, s22
	ds_read_b128 v[190:193], v145 offset:23552
	global_load_lds_dwordx4 v130, s[16:17]
	s_barrier
	s_waitcnt lgkmcnt(0)
	s_setprio 1
	v_mfma_f32_16x16x32_bf16 v[60:63], v[138:141], v[158:161], v[60:63]
	v_mfma_f32_16x16x32_bf16 v[52:55], v[150:153], v[158:161], v[52:55]
	v_mfma_f32_16x16x32_bf16 v[44:47], v[138:141], v[166:169], v[44:47]
	v_mfma_f32_16x16x32_bf16 v[36:39], v[150:153], v[166:169], v[36:39]
	v_mfma_f32_16x16x32_bf16 v[28:31], v[138:141], v[178:181], v[28:31]
	v_mfma_f32_16x16x32_bf16 v[20:23], v[150:153], v[178:181], v[20:23]
	v_mfma_f32_16x16x32_bf16 v[12:15], v[138:141], v[186:189], v[12:15]
	v_mfma_f32_16x16x32_bf16 v[4:7], v[150:153], v[186:189], v[4:7]
	v_mfma_f32_16x16x32_bf16 v[60:63], v[146:149], v[162:165], v[60:63]
	v_mfma_f32_16x16x32_bf16 v[52:55], v[154:157], v[162:165], v[52:55]
	v_mfma_f32_16x16x32_bf16 v[44:47], v[146:149], v[170:173], v[44:47]
	v_mfma_f32_16x16x32_bf16 v[36:39], v[154:157], v[170:173], v[36:39]
	v_mfma_f32_16x16x32_bf16 v[28:31], v[146:149], v[182:185], v[28:31]
	v_mfma_f32_16x16x32_bf16 v[20:23], v[154:157], v[182:185], v[20:23]
	v_mfma_f32_16x16x32_bf16 v[12:15], v[146:149], v[190:193], v[12:15]
	v_mfma_f32_16x16x32_bf16 v[4:7], v[154:157], v[190:193], v[4:7]
	s_setprio 0
	s_barrier
	s_add_u32 s46, s14, 0x40000
	s_addc_u32 s47, s15, 0
	s_add_i32 s48, s48, s20
	s_mov_b32 m0, s48
	s_nop 0
	global_load_lds_dwordx4 v176, s[46:47]
	s_add_i32 m0, s48, 0x2000
	s_nop 0
	global_load_lds_dwordx4 v128, s[46:47]
	s_waitcnt vmcnt(6)
	s_barrier
; #define PG8_STAGE(bufoff, gbase, voff) do { _Pragma("unroll") for (int _i = 0; _i < 2; ++_i) \
;         __builtin_amdgcn_global_load_lds((const unsigned*)((const char*)(gbase) + (voff)[_i]), (PG8_LAS unsigned*)(lds + (bufoff) + ldsw + _i * 8192), 16, 0, 0); } while (0)
; #define PG8_LDA(dst, b, h) do { _Pragma("unroll") for (int m = 0; m < 4; ++m) _Pragma("unroll") for (int k = 0; k < 2; ++k) dst[m][k] = *(const PG8_LAS bf16x8*)(lds + PG8_SA(b, h) + aoff + m * 2048 + k * 1024); } while (0)
; #define PG8_LDB(dst, b, h) do { _Pragma("unroll") for (int n = 0; n < 2; ++n) _Pragma("unroll") for (int k = 0; k < 2; ++k) dst[n][k] = *(const PG8_LAS bf16x8*)(lds + PG8_SB(b, h) + boff + n * 2048 + k * 1024); } while (0)
; #define PG8_MMA(ai, bj, At, Bt) do { __builtin_amdgcn_s_setprio(1); _Pragma("unroll") for (int m = 0; m < 4; ++m) _Pragma("unroll") for (int n = 0; n < 2; ++n) _Pragma("unroll") for (int k = 0; k < 2; ++k) \
;         acc[ai][bj][m][n] = __builtin_amdgcn_mfma_f32_16x16x32_bf16(Bt[n][k], At[m][k], acc[ai][bj][m][n], 0, 0, 0); __builtin_amdgcn_s_setprio(0); } while (0)
; #define PG8_WAIT_V(n) asm volatile("s_waitcnt vmcnt(" #n ")" ::: "memory")
; #define PG8_WAIT_L(n) asm volatile("s_waitcnt lgkmcnt(" #n ")" ::: "memory")
; #define PG8_BAR __builtin_amdgcn_s_barrier()
; #define PG8_SCHED __builtin_amdgcn_sched_barrier(0)
; template <class Epi, class Sched>
; __device__ __forceinline__ void gemm_phase(PG8_LAS unsigned char* lds, const Gemm g, const Sched& S, const Epi& E) {
;     ...
;             PG8_WAIT_V(6); PG8_BAR; PG8_MMA(1, 1, At, B1); PG8_BAR;
;             PG8_LDB(B0, 1, 0); PG8_SCHED; PG8_LDA(At, 1, 0); PG8_STAGE(PG8_SA(0, 1), a2 + hstep, voffA);
;             PG8_WAIT_L(8); PG8_BAR; PG8_WAIT_L(0); PG8_MMA(0, 0, At, B0); PG8_BAR; PG8_SCHED;
;             PG8_LDB(B1, 1, 1); PG8_STAGE(PG8_SB(1, 0), b3, voffB);
;             PG8_BAR; PG8_WAIT_L(0); PG8_MMA(0, 1, At, B1); PG8_BAR;
;             PG8_LDA(At, 1, 1); PG8_STAGE(PG8_SA(1, 0), a3, voffA);
;             PG8_BAR; PG8_WAIT_L(0); PG8_MMA(1, 0, At, B0); PG8_BAR; PG8_SCHED;
	s_setprio 1
	v_mfma_f32_16x16x32_bf16 v[56:59], v[194:197], v[158:161], v[56:59]
	v_mfma_f32_16x16x32_bf16 v[48:51], v[202:205], v[158:161], v[48:51]
	v_mfma_f32_16x16x32_bf16 v[40:43], v[194:197], v[166:169], v[40:43]
	v_mfma_f32_16x16x32_bf16 v[32:35], v[202:205], v[166:169], v[32:35]
	v_mfma_f32_16x16x32_bf16 v[24:27], v[194:197], v[178:181], v[24:27]
	v_mfma_f32_16x16x32_bf16 v[16:19], v[202:205], v[178:181], v[16:19]
	v_mfma_f32_16x16x32_bf16 v[8:11], v[194:197], v[186:189], v[8:11]
	v_mfma_f32_16x16x32_bf16 v[0:3], v[202:205], v[186:189], v[0:3]
	v_mfma_f32_16x16x32_bf16 v[56:59], v[198:201], v[162:165], v[56:59]
	v_mfma_f32_16x16x32_bf16 v[48:51], v[206:209], v[162:165], v[48:51]
	v_mfma_f32_16x16x32_bf16 v[40:43], v[198:201], v[170:173], v[40:43]
	v_mfma_f32_16x16x32_bf16 v[32:35], v[206:209], v[170:173], v[32:35]
	v_mfma_f32_16x16x32_bf16 v[24:27], v[198:201], v[182:185], v[24:27]
	v_mfma_f32_16x16x32_bf16 v[16:19], v[206:209], v[182:185], v[16:19]
	v_mfma_f32_16x16x32_bf16 v[8:11], v[198:201], v[190:193], v[8:11]
	v_mfma_f32_16x16x32_bf16 v[0:3], v[206:209], v[190:193], v[0:3]
	s_setprio 0
	s_add_i32 s46, 0, 0x18000
	v_add_u32_e32 v154, s46, v143
	s_barrier
	ds_read_b128 v[138:141], v154
	ds_read_b128 v[146:149], v154 offset:1024
	ds_read_b128 v[150:153], v154 offset:2048
	ds_read_b128 v[154:157], v154 offset:3072
	s_add_u32 s16, s16, 0x40000
	s_addc_u32 s17, s17, 0
	s_mov_b32 m0, s23
	ds_read_b128 v[158:161], v145 offset:32768
	ds_read_b128 v[162:165], v145 offset:33792
	ds_read_b128 v[166:169], v145 offset:34816
	ds_read_b128 v[170:173], v145 offset:35840
	ds_read_b128 v[178:181], v145 offset:36864
	ds_read_b128 v[182:185], v145 offset:37888
	ds_read_b128 v[186:189], v145 offset:38912
	global_load_lds_dwordx4 v132, s[16:17]
	s_mov_b32 m0, s26
	ds_read_b128 v[190:193], v145 offset:39936
	global_load_lds_dwordx4 v130, s[16:17]
	s_waitcnt lgkmcnt(8)
	s_barrier
	s_waitcnt lgkmcnt(0)
	s_setprio 1
	v_mfma_f32_16x16x32_bf16 v[124:127], v[138:141], v[158:161], v[124:127]
	v_mfma_f32_16x16x32_bf16 v[116:119], v[150:153], v[158:161], v[116:119]
	v_mfma_f32_16x16x32_bf16 v[108:111], v[138:141], v[166:169], v[108:111]
	v_mfma_f32_16x16x32_bf16 v[100:103], v[150:153], v[166:169], v[100:103]
	v_mfma_f32_16x16x32_bf16 v[92:95], v[138:141], v[178:181], v[92:95]
	v_mfma_f32_16x16x32_bf16 v[84:87], v[150:153], v[178:181], v[84:87]
	v_mfma_f32_16x16x32_bf16 v[76:79], v[138:141], v[186:189], v[76:79]
	v_mfma_f32_16x16x32_bf16 v[68:71], v[150:153], v[186:189], v[68:71]
	v_mfma_f32_16x16x32_bf16 v[124:127], v[146:149], v[162:165], v[124:127]
	v_mfma_f32_16x16x32_bf16 v[116:119], v[154:157], v[162:165], v[116:119]
	v_mfma_f32_16x16x32_bf16 v[108:111], v[146:149], v[170:173], v[108:111]
	v_mfma_f32_16x16x32_bf16 v[100:103], v[154:157], v[170:173], v[100:103]
	v_mfma_f32_16x16x32_bf16 v[92:95], v[146:149], v[182:185], v[92:95]
	v_mfma_f32_16x16x32_bf16 v[84:87], v[154:157], v[182:185], v[84:87]
	v_mfma_f32_16x16x32_bf16 v[76:79], v[146:149], v[190:193], v[76:79]
	v_mfma_f32_16x16x32_bf16 v[68:71], v[154:157], v[190:193], v[68:71]
	s_setprio 0
	s_barrier
	s_add_i32 s16, 0, 0x1c000
	s_add_i32 s17, s46, s20
	v_add_u32_e32 v206, s16, v143
	s_mov_b32 m0, s17
	ds_read_b128 v[194:197], v206
	ds_read_b128 v[198:201], v206 offset:1024
	ds_read_b128 v[202:205], v206 offset:2048
	global_load_lds_dwordx4 v176, s[98:99]
	s_add_i32 m0, s17, 0x2000
	ds_read_b128 v[206:209], v206 offset:3072
	global_load_lds_dwordx4 v128, s[98:99]
	s_barrier
	s_waitcnt lgkmcnt(0)
	s_setprio 1
	v_mfma_f32_16x16x32_bf16 v[120:123], v[194:197], v[158:161], v[120:123]
	v_mfma_f32_16x16x32_bf16 v[112:115], v[202:205], v[158:161], v[112:115]
	v_mfma_f32_16x16x32_bf16 v[104:107], v[194:197], v[166:169], v[104:107]
	v_mfma_f32_16x16x32_bf16 v[96:99], v[202:205], v[166:169], v[96:99]
	v_mfma_f32_16x16x32_bf16 v[88:91], v[194:197], v[178:181], v[88:91]
	v_mfma_f32_16x16x32_bf16 v[80:83], v[202:205], v[178:181], v[80:83]
	v_mfma_f32_16x16x32_bf16 v[72:75], v[194:197], v[186:189], v[72:75]
	v_mfma_f32_16x16x32_bf16 v[64:67], v[202:205], v[186:189], v[64:67]
	v_mfma_f32_16x16x32_bf16 v[120:123], v[198:201], v[162:165], v[120:123]
	v_mfma_f32_16x16x32_bf16 v[112:115], v[206:209], v[162:165], v[112:115]
	v_mfma_f32_16x16x32_bf16 v[104:107], v[198:201], v[170:173], v[104:107]
	v_mfma_f32_16x16x32_bf16 v[96:99], v[206:209], v[170:173], v[96:99]
	v_mfma_f32_16x16x32_bf16 v[88:91], v[198:201], v[182:185], v[88:91]
	v_mfma_f32_16x16x32_bf16 v[80:83], v[206:209], v[182:185], v[80:83]
	v_mfma_f32_16x16x32_bf16 v[72:75], v[198:201], v[190:193], v[72:75]
	v_mfma_f32_16x16x32_bf16 v[64:67], v[206:209], v[190:193], v[64:67]
	s_setprio 0
	s_mov_b32 m0, s28
	s_barrier
	ds_read_b128 v[158:161], v145 offset:49152
	ds_read_b128 v[162:165], v145 offset:50176
	ds_read_b128 v[166:169], v145 offset:51200
	ds_read_b128 v[170:173], v145 offset:52224
	ds_read_b128 v[178:181], v145 offset:53248
	ds_read_b128 v[182:185], v145 offset:54272
	ds_read_b128 v[186:189], v145 offset:55296
	global_load_lds_dwordx4 v132, s[100:101]
	s_mov_b32 m0, s29
	ds_read_b128 v[190:193], v145 offset:56320
	global_load_lds_dwordx4 v130, s[100:101]
	s_barrier
; __device__ __forceinline__ unsigned cvtpk(float lo, float hi) { const f32x2 v = (f32x2){lo, hi}; const bf16v2 b = __builtin_convertvector(v, bf16v2); return __builtin_bit_cast(unsigned, b); }
; __device__ __forceinline__ float siluf_(float x) { return x * sigmoidf_(x); }
; #define PG8_STAGE(bufoff, gbase, voff) do { _Pragma("unroll") for (int _i = 0; _i < 2; ++_i) \
;         __builtin_amdgcn_global_load_lds((const unsigned*)((const char*)(gbase) + (voff)[_i]), (PG8_LAS unsigned*)(lds + (bufoff) + ldsw + _i * 8192), 16, 0, 0); } while (0)
; #define PG8_MMA(ai, bj, At, Bt) do { __builtin_amdgcn_s_setprio(1); _Pragma("unroll") for (int m = 0; m < 4; ++m) _Pragma("unroll") for (int n = 0; n < 2; ++n) _Pragma("unroll") for (int k = 0; k < 2; ++k) \
;         acc[ai][bj][m][n] = __builtin_amdgcn_mfma_f32_16x16x32_bf16(Bt[n][k], At[m][k], acc[ai][bj][m][n], 0, 0, 0); __builtin_amdgcn_s_setprio(0); } while (0)
; #define PG8_WAIT_V(n) asm volatile("s_waitcnt vmcnt(" #n ")" ::: "memory")
; #define PG8_BAR __builtin_amdgcn_s_barrier()
; template <class Epi, class Sched>
; __device__ __forceinline__ void gemm_phase(PG8_LAS unsigned char* lds, const Gemm g, const Sched& S, const Epi& E) {
;     ...
;             PG8_BAR; PG8_WAIT_L(0); PG8_MMA(1, 0, At, B0); PG8_BAR; PG8_SCHED;
;             PG8_STAGE(PG8_SB(1, 1), b3 + hstep, voffB);
;             PG8_WAIT_V(6); PG8_BAR; PG8_MMA(1, 1, At, B1); PG8_BAR;
;         }
;         if constexpr (!Epi::AFTER_DRAIN) { E(acc, cur, wr, wc, fr, fq); S.done(cur); }
;     __device__ __forceinline__ void operator()(const f32x4 (&acc)[2][2][4][2], const pg8::Unit& u, int wr, int wc, int fr, int fq) const {
;         const int row0 = u.pm * 256 + wr * 64 + fr, col0 = u.pn * 128 + wc * 32 + 8 * fq;
; #pragma unroll
;         for (int ai = 0; ai < 2; ++ai)
; #pragma unroll
;             for (int m = 0; m < 4; ++m) { bf16_t* rowp = O + (size_t)(row0 + ai * 128 + m * 16) * ldc + col0;
;                 const f32x4 g0 = acc[ai][0][m][0], g1 = acc[ai][0][m][1], u0 = acc[ai][1][m][0], u1 = acc[ai][1][m][1];
;                 u32x4 w; w.x = cvtpk(siluf_(g0[0]) * u0[0], siluf_(g0[1]) * u0[1]); w.y = cvtpk(siluf_(g0[2]) * u0[2], siluf_(g0[3]) * u0[3]);
;                 w.z = cvtpk(siluf_(g1[0]) * u1[0], siluf_(g1[1]) * u1[1]); w.w = cvtpk(siluf_(g1[2]) * u1[2], siluf_(g1[3]) * u1[3]);
;                 *(u32x4*)rowp = w; }
	s_waitcnt lgkmcnt(0)
	s_setprio 1
	v_mfma_f32_16x16x32_bf16 v[60:63], v[138:141], v[158:161], v[60:63]
	v_mfma_f32_16x16x32_bf16 v[52:55], v[150:153], v[158:161], v[52:55]
	v_mfma_f32_16x16x32_bf16 v[44:47], v[138:141], v[166:169], v[44:47]
	v_mfma_f32_16x16x32_bf16 v[36:39], v[150:153], v[166:169], v[36:39]
	v_mfma_f32_16x16x32_bf16 v[28:31], v[138:141], v[178:181], v[28:31]
	v_mfma_f32_16x16x32_bf16 v[20:23], v[150:153], v[178:181], v[20:23]
	v_mfma_f32_16x16x32_bf16 v[12:15], v[138:141], v[186:189], v[12:15]
	v_mfma_f32_16x16x32_bf16 v[4:7], v[150:153], v[186:189], v[4:7]
	v_mfma_f32_16x16x32_bf16 v[60:63], v[146:149], v[162:165], v[60:63]
	v_mfma_f32_16x16x32_bf16 v[52:55], v[154:157], v[162:165], v[52:55]
	v_mfma_f32_16x16x32_bf16 v[44:47], v[146:149], v[170:173], v[44:47]
	v_mfma_f32_16x16x32_bf16 v[36:39], v[154:157], v[170:173], v[36:39]
	v_mfma_f32_16x16x32_bf16 v[28:31], v[146:149], v[182:185], v[28:31]
	v_mfma_f32_16x16x32_bf16 v[20:23], v[154:157], v[182:185], v[20:23]
	v_mfma_f32_16x16x32_bf16 v[12:15], v[146:149], v[190:193], v[12:15]
	v_mfma_f32_16x16x32_bf16 v[4:7], v[154:157], v[190:193], v[4:7]
	s_setprio 0
	s_barrier
	s_add_u32 s14, s14, 0x40080
	s_addc_u32 s15, s15, 0
	s_add_i32 s16, s16, s20
	s_mov_b32 m0, s16
	s_nop 0
	global_load_lds_dwordx4 v176, s[14:15]
	s_add_i32 m0, s16, 0x2000
	s_nop 0
	global_load_lds_dwordx4 v128, s[14:15]
	s_waitcnt vmcnt(6)
	s_barrier
	s_setprio 1
	v_mfma_f32_16x16x32_bf16 v[56:59], v[194:197], v[158:161], v[56:59]
	v_mfma_f32_16x16x32_bf16 v[48:51], v[202:205], v[158:161], v[48:51]
	v_mfma_f32_16x16x32_bf16 v[40:43], v[194:197], v[166:169], v[40:43]
	v_mfma_f32_16x16x32_bf16 v[32:35], v[202:205], v[166:169], v[32:35]
	v_mfma_f32_16x16x32_bf16 v[24:27], v[194:197], v[178:181], v[24:27]
	v_mfma_f32_16x16x32_bf16 v[16:19], v[202:205], v[178:181], v[16:19]
	v_mfma_f32_16x16x32_bf16 v[8:11], v[194:197], v[186:189], v[8:11]
	v_mfma_f32_16x16x32_bf16 v[0:3], v[202:205], v[186:189], v[0:3]
	v_mfma_f32_16x16x32_bf16 v[56:59], v[198:201], v[162:165], v[56:59]
	v_mfma_f32_16x16x32_bf16 v[48:51], v[206:209], v[162:165], v[48:51]
	v_mfma_f32_16x16x32_bf16 v[40:43], v[198:201], v[170:173], v[40:43]
	v_mfma_f32_16x16x32_bf16 v[32:35], v[206:209], v[170:173], v[32:35]
	v_mfma_f32_16x16x32_bf16 v[24:27], v[198:201], v[182:185], v[24:27]
	v_mfma_f32_16x16x32_bf16 v[16:19], v[206:209], v[182:185], v[16:19]
	v_mfma_f32_16x16x32_bf16 v[8:11], v[198:201], v[190:193], v[8:11]
	v_mfma_f32_16x16x32_bf16 v[0:3], v[206:209], v[190:193], v[0:3]
	s_setprio 0
	s_add_i32 s45, s45, 2
	s_add_u32 s12, s12, 0x100
	s_addc_u32 s13, s13, 0
	s_add_u32 s43, s43, 0x100
	s_addc_u32 s44, s44, 0
	s_cmp_gt_u32 s45, 13
	s_barrier
	s_cbranch_scc0 .LBB0_114
	v_mul_f32_e32 v147, 0xbfb8aa3b, v124
	v_exp_f32_e32 v147, v147
	v_readlane_b32 s12, v253, 16
	v_lshl_add_u32 v146, s10, 8, v142
	v_lshl_or_b32 v140, s34, 7, v144
	v_add_f32_e32 v147, 1.0, v147
	v_rcp_f32_e32 v150, v147
	v_mul_f32_e32 v147, 0xbfb8aa3b, v125
	v_exp_f32_e32 v147, v147
	v_readlane_b32 s13, v253, 17
	v_ashrrev_i32_e32 v141, 31, v140
	v_lshlrev_b64 v[140:141], 1, v[140:141]
	v_add_f32_e32 v147, 1.0, v147
	v_rcp_f32_e32 v151, v147
	v_mov_b64_e32 v[138:139], s[12:13]
	v_mad_i64_i32 v[148:149], s[12:13], v146, s81, v[138:139]
	v_pk_mul_f32 v[124:125], v[124:125], v[150:151]
	v_lshl_add_u64 v[148:149], v[148:149], 0, v[140:141]
	v_pk_mul_f32 v[120:121], v[124:125], v[120:121]
	s_and_b64 vcc, exec, s[38:39]
	v_cvt_pk_bf16_f32 v120, v120, v121
	v_mul_f32_e32 v121, 0xbfb8aa3b, v126
	v_exp_f32_e32 v121, v121
	s_mov_b32 s34, s0
	s_mov_b32 s10, s4
	s_mov_b64 s[14:15], s[8:9]
	v_add_f32_e32 v121, 1.0, v121
	v_rcp_f32_e32 v124, v121
	v_mul_f32_e32 v121, 0xbfb8aa3b, v127
	v_exp_f32_e32 v121, v121
	s_nop 0
	v_add_f32_e32 v121, 1.0, v121
	v_rcp_f32_e32 v125, v121
	s_nop 0
	v_pk_mul_f32 v[124:125], v[126:127], v[124:125]
	s_nop 0
	v_pk_mul_f32 v[122:123], v[124:125], v[122:123]
	s_nop 0
	v_cvt_pk_bf16_f32 v121, v122, v123
	v_mul_f32_e32 v122, 0xbfb8aa3b, v116
	v_mul_f32_e32 v123, 0xbfb8aa3b, v117
	v_exp_f32_e32 v122, v122
	v_exp_f32_e32 v123, v123
	v_add_f32_e32 v122, 1.0, v122
	v_add_f32_e32 v123, 1.0, v123
	v_rcp_f32_e32 v122, v122
	v_rcp_f32_e32 v123, v123
	s_nop 0
	v_pk_mul_f32 v[116:117], v[116:117], v[122:123]
	s_nop 0
	v_pk_mul_f32 v[112:113], v[116:117], v[112:113]
	s_nop 0
	v_cvt_pk_bf16_f32 v122, v112, v113
	v_mul_f32_e32 v112, 0xbfb8aa3b, v118
	v_mul_f32_e32 v113, 0xbfb8aa3b, v119
	v_exp_f32_e32 v112, v112
	v_exp_f32_e32 v113, v113
	v_add_f32_e32 v112, 1.0, v112
	v_add_f32_e32 v113, 1.0, v113
	v_rcp_f32_e32 v112, v112
	v_rcp_f32_e32 v113, v113
	s_nop 0
	v_pk_mul_f32 v[112:113], v[118:119], v[112:113]
	s_nop 0
	v_pk_mul_f32 v[112:113], v[112:113], v[114:115]
	v_mul_f32_e32 v114, 0xbfb8aa3b, v108
	v_mul_f32_e32 v115, 0xbfb8aa3b, v109
	v_exp_f32_e32 v114, v114
	v_exp_f32_e32 v115, v115
	v_cvt_pk_bf16_f32 v123, v112, v113
	v_or_b32_e32 v112, 16, v146
	v_add_f32_e32 v114, 1.0, v114
	v_add_f32_e32 v115, 1.0, v115
	v_rcp_f32_e32 v114, v114
	v_rcp_f32_e32 v115, v115
	v_mad_i64_i32 v[112:113], s[12:13], v112, s81, v[138:139]
	v_lshl_add_u64 v[112:113], v[112:113], 0, v[140:141]
	v_pk_mul_f32 v[108:109], v[108:109], v[114:115]
	global_store_dwordx4 v[148:149], v[120:123], off
	v_pk_mul_f32 v[104:105], v[108:109], v[104:105]
	s_nop 0
	v_cvt_pk_bf16_f32 v104, v104, v105
	v_mul_f32_e32 v105, 0xbfb8aa3b, v110
	v_exp_f32_e32 v105, v105
	s_nop 0
	v_add_f32_e32 v105, 1.0, v105
	v_rcp_f32_e32 v108, v105
	v_mul_f32_e32 v105, 0xbfb8aa3b, v111
	v_exp_f32_e32 v105, v105
	s_nop 0
	v_add_f32_e32 v105, 1.0, v105
	v_rcp_f32_e32 v109, v105
	s_nop 0
	v_pk_mul_f32 v[108:109], v[110:111], v[108:109]
; __device__ __forceinline__ unsigned cvtpk(float lo, float hi) { const f32x2 v = (f32x2){lo, hi}; const bf16v2 b = __builtin_convertvector(v, bf16v2); return __builtin_bit_cast(unsigned, b); }
; __device__ __forceinline__ float siluf_(float x) { return x * sigmoidf_(x); }
;     __device__ __forceinline__ void operator()(const f32x4 (&acc)[2][2][4][2], const pg8::Unit& u, int wr, int wc, int fr, int fq) const {
;         const int row0 = u.pm * 256 + wr * 64 + fr, col0 = u.pn * 128 + wc * 32 + 8 * fq;
; #pragma unroll
;         for (int ai = 0; ai < 2; ++ai)
; #pragma unroll
;             for (int m = 0; m < 4; ++m) { bf16_t* rowp = O + (size_t)(row0 + ai * 128 + m * 16) * ldc + col0;
;                 const f32x4 g0 = acc[ai][0][m][0], g1 = acc[ai][0][m][1], u0 = acc[ai][1][m][0], u1 = acc[ai][1][m][1];
;                 u32x4 w; w.x = cvtpk(siluf_(g0[0]) * u0[0], siluf_(g0[1]) * u0[1]); w.y = cvtpk(siluf_(g0[2]) * u0[2], siluf_(g0[3]) * u0[3]);
;                 w.z = cvtpk(siluf_(g1[0]) * u1[0], siluf_(g1[1]) * u1[1]); w.w = cvtpk(siluf_(g1[2]) * u1[2], siluf_(g1[3]) * u1[3]);
;                 *(u32x4*)rowp = w; }
	s_nop 0
	v_pk_mul_f32 v[106:107], v[108:109], v[106:107]
	s_nop 0
	v_cvt_pk_bf16_f32 v105, v106, v107
	v_mul_f32_e32 v106, 0xbfb8aa3b, v100
	v_mul_f32_e32 v107, 0xbfb8aa3b, v101
	v_exp_f32_e32 v106, v106
	v_exp_f32_e32 v107, v107
	v_add_f32_e32 v106, 1.0, v106
	v_add_f32_e32 v107, 1.0, v107
	v_rcp_f32_e32 v106, v106
	v_rcp_f32_e32 v107, v107
	s_nop 0
	v_pk_mul_f32 v[100:101], v[100:101], v[106:107]
	s_nop 0
	v_pk_mul_f32 v[96:97], v[100:101], v[96:97]
	s_nop 0
	v_cvt_pk_bf16_f32 v106, v96, v97
	v_mul_f32_e32 v96, 0xbfb8aa3b, v102
	v_mul_f32_e32 v97, 0xbfb8aa3b, v103
	v_exp_f32_e32 v96, v96
	v_exp_f32_e32 v97, v97
	v_add_f32_e32 v96, 1.0, v96
	v_add_f32_e32 v97, 1.0, v97
	v_rcp_f32_e32 v96, v96
	v_rcp_f32_e32 v97, v97
	s_nop 0
	v_pk_mul_f32 v[96:97], v[102:103], v[96:97]
	s_nop 0
	v_pk_mul_f32 v[96:97], v[96:97], v[98:99]
	v_mul_f32_e32 v98, 0xbfb8aa3b, v92
	v_mul_f32_e32 v99, 0xbfb8aa3b, v93
	v_exp_f32_e32 v98, v98
	v_exp_f32_e32 v99, v99
	v_cvt_pk_bf16_f32 v107, v96, v97
	v_or_b32_e32 v96, 32, v146
	v_add_f32_e32 v98, 1.0, v98
	v_add_f32_e32 v99, 1.0, v99
	v_rcp_f32_e32 v98, v98
	v_rcp_f32_e32 v99, v99
	v_mad_i64_i32 v[96:97], s[12:13], v96, s81, v[138:139]
	v_lshl_add_u64 v[96:97], v[96:97], 0, v[140:141]
	v_pk_mul_f32 v[92:93], v[92:93], v[98:99]
	global_store_dwordx4 v[112:113], v[104:107], off
	v_pk_mul_f32 v[88:89], v[92:93], v[88:89]
	s_nop 0
	v_cvt_pk_bf16_f32 v88, v88, v89
	v_mul_f32_e32 v89, 0xbfb8aa3b, v94
	v_exp_f32_e32 v89, v89
	s_nop 0
	v_add_f32_e32 v89, 1.0, v89
	v_rcp_f32_e32 v92, v89
	v_mul_f32_e32 v89, 0xbfb8aa3b, v95
	v_exp_f32_e32 v89, v89
	s_nop 0
	v_add_f32_e32 v89, 1.0, v89
	v_rcp_f32_e32 v93, v89
	s_nop 0
	v_pk_mul_f32 v[92:93], v[94:95], v[92:93]
	s_nop 0
	v_pk_mul_f32 v[90:91], v[92:93], v[90:91]
	s_nop 0
	v_cvt_pk_bf16_f32 v89, v90, v91
	v_mul_f32_e32 v90, 0xbfb8aa3b, v84
	v_mul_f32_e32 v91, 0xbfb8aa3b, v85
	v_exp_f32_e32 v90, v90
	v_exp_f32_e32 v91, v91
	v_add_f32_e32 v90, 1.0, v90
	v_add_f32_e32 v91, 1.0, v91
	v_rcp_f32_e32 v90, v90
	v_rcp_f32_e32 v91, v91
	s_nop 0
	v_pk_mul_f32 v[84:85], v[84:85], v[90:91]
	s_nop 0
	v_pk_mul_f32 v[80:81], v[84:85], v[80:81]
	s_nop 0
	v_cvt_pk_bf16_f32 v90, v80, v81
	v_mul_f32_e32 v80, 0xbfb8aa3b, v86
	v_mul_f32_e32 v81, 0xbfb8aa3b, v87
	v_exp_f32_e32 v80, v80
	v_exp_f32_e32 v81, v81
	v_add_f32_e32 v80, 1.0, v80
	v_add_f32_e32 v81, 1.0, v81
	v_rcp_f32_e32 v80, v80
	v_rcp_f32_e32 v81, v81
	s_nop 0
	v_pk_mul_f32 v[80:81], v[86:87], v[80:81]
	s_nop 0
	v_pk_mul_f32 v[80:81], v[80:81], v[82:83]
	v_mul_f32_e32 v82, 0xbfb8aa3b, v76
	v_mul_f32_e32 v83, 0xbfb8aa3b, v77
	v_exp_f32_e32 v82, v82
	v_exp_f32_e32 v83, v83
	v_cvt_pk_bf16_f32 v91, v80, v81
	v_or_b32_e32 v80, 48, v146
	v_add_f32_e32 v82, 1.0, v82
	v_add_f32_e32 v83, 1.0, v83
	v_rcp_f32_e32 v82, v82
	v_rcp_f32_e32 v83, v83
	v_mad_i64_i32 v[80:81], s[12:13], v80, s81, v[138:139]
	v_lshl_add_u64 v[80:81], v[80:81], 0, v[140:141]
	v_pk_mul_f32 v[76:77], v[76:77], v[82:83]
	global_store_dwordx4 v[96:97], v[88:91], off
	v_pk_mul_f32 v[72:73], v[76:77], v[72:73]
	s_nop 0
	v_cvt_pk_bf16_f32 v72, v72, v73
	v_mul_f32_e32 v73, 0xbfb8aa3b, v78
	v_exp_f32_e32 v73, v73
	s_nop 0
	v_add_f32_e32 v73, 1.0, v73
	v_rcp_f32_e32 v76, v73
	v_mul_f32_e32 v73, 0xbfb8aa3b, v79
	v_exp_f32_e32 v73, v73
	s_nop 0
	v_add_f32_e32 v73, 1.0, v73
	v_rcp_f32_e32 v77, v73
	s_nop 0
	v_pk_mul_f32 v[76:77], v[78:79], v[76:77]
	s_nop 0
	v_pk_mul_f32 v[74:75], v[76:77], v[74:75]
	s_nop 0
	v_cvt_pk_bf16_f32 v73, v74, v75
	v_mul_f32_e32 v74, 0xbfb8aa3b, v68
	v_mul_f32_e32 v75, 0xbfb8aa3b, v69
	v_exp_f32_e32 v74, v74
	v_exp_f32_e32 v75, v75
	v_add_f32_e32 v74, 1.0, v74
	v_add_f32_e32 v75, 1.0, v75
	v_rcp_f32_e32 v74, v74
	v_rcp_f32_e32 v75, v75
	s_nop 0
	v_pk_mul_f32 v[68:69], v[68:69], v[74:75]
	s_nop 0
	v_pk_mul_f32 v[64:65], v[68:69], v[64:65]
	s_nop 0
	v_cvt_pk_bf16_f32 v74, v64, v65
	v_mul_f32_e32 v64, 0xbfb8aa3b, v70
	v_mul_f32_e32 v65, 0xbfb8aa3b, v71
	v_exp_f32_e32 v64, v64
	v_exp_f32_e32 v65, v65
	v_add_f32_e32 v64, 1.0, v64
	v_add_f32_e32 v65, 1.0, v65
	v_rcp_f32_e32 v64, v64
	v_rcp_f32_e32 v65, v65
	s_nop 0
	v_pk_mul_f32 v[64:65], v[70:71], v[64:65]
	s_nop 0
	v_pk_mul_f32 v[64:65], v[64:65], v[66:67]
	v_mul_f32_e32 v66, 0xbfb8aa3b, v60
	v_mul_f32_e32 v67, 0xbfb8aa3b, v61
	v_exp_f32_e32 v66, v66
	v_exp_f32_e32 v67, v67
	v_cvt_pk_bf16_f32 v75, v64, v65
	v_add_u32_e32 v64, 0x80, v146
	v_add_f32_e32 v66, 1.0, v66
	v_add_f32_e32 v67, 1.0, v67
	v_rcp_f32_e32 v66, v66
	v_rcp_f32_e32 v67, v67
	v_mad_i64_i32 v[64:65], s[12:13], v64, s81, v[138:139]
	v_lshl_add_u64 v[64:65], v[64:65], 0, v[140:141]
	v_pk_mul_f32 v[60:61], v[60:61], v[66:67]
	global_store_dwordx4 v[80:81], v[72:75], off
	v_pk_mul_f32 v[56:57], v[60:61], v[56:57]
	s_nop 0
	v_cvt_pk_bf16_f32 v56, v56, v57
	v_mul_f32_e32 v57, 0xbfb8aa3b, v62
	v_exp_f32_e32 v57, v57
	s_nop 0
	v_add_f32_e32 v57, 1.0, v57
	v_rcp_f32_e32 v60, v57
	v_mul_f32_e32 v57, 0xbfb8aa3b, v63
	v_exp_f32_e32 v57, v57
	s_nop 0
	v_add_f32_e32 v57, 1.0, v57
	v_rcp_f32_e32 v61, v57
	s_nop 0
	v_pk_mul_f32 v[60:61], v[62:63], v[60:61]
	s_nop 0
	v_pk_mul_f32 v[58:59], v[60:61], v[58:59]
	s_nop 0
	v_cvt_pk_bf16_f32 v57, v58, v59
	v_mul_f32_e32 v58, 0xbfb8aa3b, v52
	v_mul_f32_e32 v59, 0xbfb8aa3b, v53
	v_exp_f32_e32 v58, v58
	v_exp_f32_e32 v59, v59
	v_add_f32_e32 v58, 1.0, v58
	v_add_f32_e32 v59, 1.0, v59
	v_rcp_f32_e32 v58, v58
	v_rcp_f32_e32 v59, v59
	s_nop 0
	v_pk_mul_f32 v[52:53], v[52:53], v[58:59]
	s_nop 0
	v_pk_mul_f32 v[48:49], v[52:53], v[48:49]
	s_nop 0
	v_cvt_pk_bf16_f32 v58, v48, v49
	v_mul_f32_e32 v48, 0xbfb8aa3b, v54
; __device__ __forceinline__ unsigned cvtpk(float lo, float hi) { const f32x2 v = (f32x2){lo, hi}; const bf16v2 b = __builtin_convertvector(v, bf16v2); return __builtin_bit_cast(unsigned, b); }
; __device__ __forceinline__ float siluf_(float x) { return x * sigmoidf_(x); }
; #define PG8_WAIT_V(n) asm volatile("s_waitcnt vmcnt(" #n ")" ::: "memory")
; #define PG8_BAR __builtin_amdgcn_s_barrier()
; template <class Epi, class Sched>
; __device__ __forceinline__ void gemm_phase(PG8_LAS unsigned char* lds, const Gemm g, const Sched& S, const Epi& E) {
;     ...
;         if constexpr (!Epi::AFTER_DRAIN) { E(acc, cur, wr, wc, fr, fq); S.done(cur); }
;         if (!has_next) break;
; #pragma unroll
;         for (int a = 0; a < 2; ++a)
; #pragma unroll
;             for (int b = 0; b < 2; ++b)
; #pragma unroll
;                 for (int m = 0; m < 4; ++m)
; #pragma unroll
;                     for (int n = 0; n < 2; ++n) acc[a][b][m][n] = (f32x4){0.f, 0.f, 0.f, 0.f};
;         cur = nxt; cA = nA; cB = nB; ++ui;
;     }
;     PG8_WAIT_V(0);
;     if (wr == 0) PG8_BAR;
;     __device__ __forceinline__ void operator()(const f32x4 (&acc)[2][2][4][2], const pg8::Unit& u, int wr, int wc, int fr, int fq) const {
;         const int row0 = u.pm * 256 + wr * 64 + fr, col0 = u.pn * 128 + wc * 32 + 8 * fq;
; #pragma unroll
;         for (int ai = 0; ai < 2; ++ai)
; #pragma unroll
;             for (int m = 0; m < 4; ++m) { bf16_t* rowp = O + (size_t)(row0 + ai * 128 + m * 16) * ldc + col0;
;                 const f32x4 g0 = acc[ai][0][m][0], g1 = acc[ai][0][m][1], u0 = acc[ai][1][m][0], u1 = acc[ai][1][m][1];
;                 u32x4 w; w.x = cvtpk(siluf_(g0[0]) * u0[0], siluf_(g0[1]) * u0[1]); w.y = cvtpk(siluf_(g0[2]) * u0[2], siluf_(g0[3]) * u0[3]);
;                 w.z = cvtpk(siluf_(g1[0]) * u1[0], siluf_(g1[1]) * u1[1]); w.w = cvtpk(siluf_(g1[2]) * u1[2], siluf_(g1[3]) * u1[3]);
;                 *(u32x4*)rowp = w; }
	v_mul_f32_e32 v49, 0xbfb8aa3b, v55
	v_exp_f32_e32 v48, v48
	v_exp_f32_e32 v49, v49
	v_add_f32_e32 v48, 1.0, v48
	v_add_f32_e32 v49, 1.0, v49
	v_rcp_f32_e32 v48, v48
	v_rcp_f32_e32 v49, v49
	s_nop 0
	v_pk_mul_f32 v[48:49], v[54:55], v[48:49]
	s_nop 0
	v_pk_mul_f32 v[48:49], v[48:49], v[50:51]
	v_mul_f32_e32 v50, 0xbfb8aa3b, v44
	v_mul_f32_e32 v51, 0xbfb8aa3b, v45
	v_exp_f32_e32 v50, v50
	v_exp_f32_e32 v51, v51
	v_cvt_pk_bf16_f32 v59, v48, v49
	v_add_u32_e32 v48, 0x90, v146
	v_add_f32_e32 v50, 1.0, v50
	v_add_f32_e32 v51, 1.0, v51
	v_rcp_f32_e32 v50, v50
	v_rcp_f32_e32 v51, v51
	v_mad_i64_i32 v[48:49], s[12:13], v48, s81, v[138:139]
	v_lshl_add_u64 v[48:49], v[48:49], 0, v[140:141]
	v_pk_mul_f32 v[44:45], v[44:45], v[50:51]
	global_store_dwordx4 v[64:65], v[56:59], off
	v_pk_mul_f32 v[40:41], v[44:45], v[40:41]
	s_nop 0
	v_cvt_pk_bf16_f32 v40, v40, v41
	v_mul_f32_e32 v41, 0xbfb8aa3b, v46
	v_exp_f32_e32 v41, v41
	s_nop 0
	v_add_f32_e32 v41, 1.0, v41
	v_rcp_f32_e32 v44, v41
	v_mul_f32_e32 v41, 0xbfb8aa3b, v47
	v_exp_f32_e32 v41, v41
	s_nop 0
	v_add_f32_e32 v41, 1.0, v41
	v_rcp_f32_e32 v45, v41
	s_nop 0
	v_pk_mul_f32 v[44:45], v[46:47], v[44:45]
	s_nop 0
	v_pk_mul_f32 v[42:43], v[44:45], v[42:43]
	s_nop 0
	v_cvt_pk_bf16_f32 v41, v42, v43
	v_mul_f32_e32 v42, 0xbfb8aa3b, v36
	v_mul_f32_e32 v43, 0xbfb8aa3b, v37
	v_exp_f32_e32 v42, v42
	v_exp_f32_e32 v43, v43
	v_add_f32_e32 v42, 1.0, v42
	v_add_f32_e32 v43, 1.0, v43
	v_rcp_f32_e32 v42, v42
	v_rcp_f32_e32 v43, v43
	s_nop 0
	v_pk_mul_f32 v[36:37], v[36:37], v[42:43]
	s_nop 0
	v_pk_mul_f32 v[32:33], v[36:37], v[32:33]
	s_nop 0
	v_cvt_pk_bf16_f32 v42, v32, v33
	v_mul_f32_e32 v32, 0xbfb8aa3b, v38
	v_mul_f32_e32 v33, 0xbfb8aa3b, v39
	v_exp_f32_e32 v32, v32
	v_exp_f32_e32 v33, v33
	v_add_f32_e32 v32, 1.0, v32
	v_add_f32_e32 v33, 1.0, v33
	v_rcp_f32_e32 v32, v32
	v_rcp_f32_e32 v33, v33
	s_nop 0
	v_pk_mul_f32 v[32:33], v[38:39], v[32:33]
	s_nop 0
	v_pk_mul_f32 v[32:33], v[32:33], v[34:35]
	v_mul_f32_e32 v34, 0xbfb8aa3b, v28
	v_mul_f32_e32 v35, 0xbfb8aa3b, v29
	v_exp_f32_e32 v34, v34
	v_exp_f32_e32 v35, v35
	v_cvt_pk_bf16_f32 v43, v32, v33
	v_add_u32_e32 v32, 0xa0, v146
	v_add_f32_e32 v34, 1.0, v34
	v_add_f32_e32 v35, 1.0, v35
	v_rcp_f32_e32 v34, v34
	v_rcp_f32_e32 v35, v35
	v_mad_i64_i32 v[32:33], s[12:13], v32, s81, v[138:139]
	v_lshl_add_u64 v[32:33], v[32:33], 0, v[140:141]
	v_pk_mul_f32 v[28:29], v[28:29], v[34:35]
	global_store_dwordx4 v[48:49], v[40:43], off
	v_pk_mul_f32 v[24:25], v[28:29], v[24:25]
	s_nop 0
	v_cvt_pk_bf16_f32 v24, v24, v25
	v_mul_f32_e32 v25, 0xbfb8aa3b, v30
	v_exp_f32_e32 v25, v25
	s_nop 0
	v_add_f32_e32 v25, 1.0, v25
	v_rcp_f32_e32 v28, v25
	v_mul_f32_e32 v25, 0xbfb8aa3b, v31
	v_exp_f32_e32 v25, v25
	s_nop 0
	v_add_f32_e32 v25, 1.0, v25
	v_rcp_f32_e32 v29, v25
	s_nop 0
	v_pk_mul_f32 v[28:29], v[30:31], v[28:29]
	s_nop 0
	v_pk_mul_f32 v[26:27], v[28:29], v[26:27]
	s_nop 0
	v_cvt_pk_bf16_f32 v25, v26, v27
	v_mul_f32_e32 v26, 0xbfb8aa3b, v20
	v_mul_f32_e32 v27, 0xbfb8aa3b, v21
	v_exp_f32_e32 v26, v26
	v_exp_f32_e32 v27, v27
	v_add_f32_e32 v26, 1.0, v26
	v_add_f32_e32 v27, 1.0, v27
	v_rcp_f32_e32 v26, v26
	v_rcp_f32_e32 v27, v27
	s_nop 0
	v_pk_mul_f32 v[20:21], v[20:21], v[26:27]
	s_nop 0
	v_pk_mul_f32 v[16:17], v[20:21], v[16:17]
	s_nop 0
	v_cvt_pk_bf16_f32 v26, v16, v17
	v_mul_f32_e32 v16, 0xbfb8aa3b, v22
	v_mul_f32_e32 v17, 0xbfb8aa3b, v23
	v_exp_f32_e32 v16, v16
	v_exp_f32_e32 v17, v17
	v_add_f32_e32 v16, 1.0, v16
	v_add_f32_e32 v17, 1.0, v17
	v_rcp_f32_e32 v16, v16
	v_rcp_f32_e32 v17, v17
	s_nop 0
	v_pk_mul_f32 v[16:17], v[22:23], v[16:17]
	s_nop 0
	v_pk_mul_f32 v[16:17], v[16:17], v[18:19]
	v_mul_f32_e32 v18, 0xbfb8aa3b, v12
	v_mul_f32_e32 v19, 0xbfb8aa3b, v13
	v_exp_f32_e32 v18, v18
	v_exp_f32_e32 v19, v19
	v_cvt_pk_bf16_f32 v27, v16, v17
	v_add_u32_e32 v16, 0xb0, v146
	v_add_f32_e32 v18, 1.0, v18
	v_add_f32_e32 v19, 1.0, v19
	v_rcp_f32_e32 v18, v18
	v_rcp_f32_e32 v19, v19
	v_mad_i64_i32 v[16:17], s[12:13], v16, s81, v[138:139]
	v_lshl_add_u64 v[16:17], v[16:17], 0, v[140:141]
	v_pk_mul_f32 v[12:13], v[12:13], v[18:19]
	s_mov_b64 s[12:13], s[6:7]
	v_pk_mul_f32 v[8:9], v[12:13], v[8:9]
	global_store_dwordx4 v[32:33], v[24:27], off
	v_cvt_pk_bf16_f32 v8, v8, v9
	v_mul_f32_e32 v9, 0xbfb8aa3b, v14
	v_exp_f32_e32 v9, v9
	s_nop 0
	v_add_f32_e32 v9, 1.0, v9
	v_rcp_f32_e32 v12, v9
	v_mul_f32_e32 v9, 0xbfb8aa3b, v15
	v_exp_f32_e32 v9, v9
	s_nop 0
	v_add_f32_e32 v9, 1.0, v9
	v_rcp_f32_e32 v13, v9
	s_nop 0
	v_pk_mul_f32 v[12:13], v[14:15], v[12:13]
	s_nop 0
	v_pk_mul_f32 v[10:11], v[12:13], v[10:11]
	s_nop 0
	v_cvt_pk_bf16_f32 v9, v10, v11
	v_mul_f32_e32 v10, 0xbfb8aa3b, v4
	v_mul_f32_e32 v11, 0xbfb8aa3b, v5
	v_exp_f32_e32 v10, v10
	v_exp_f32_e32 v11, v11
	v_add_f32_e32 v10, 1.0, v10
	v_add_f32_e32 v11, 1.0, v11
	v_rcp_f32_e32 v10, v10
	v_rcp_f32_e32 v11, v11
	s_nop 0
	v_pk_mul_f32 v[4:5], v[4:5], v[10:11]
	s_nop 0
	v_pk_mul_f32 v[0:1], v[4:5], v[0:1]
	s_nop 0
	v_cvt_pk_bf16_f32 v10, v0, v1
	v_mul_f32_e32 v0, 0xbfb8aa3b, v6
	v_mul_f32_e32 v1, 0xbfb8aa3b, v7
	v_exp_f32_e32 v0, v0
	v_exp_f32_e32 v1, v1
	v_add_f32_e32 v0, 1.0, v0
	v_add_f32_e32 v1, 1.0, v1
	v_rcp_f32_e32 v0, v0
	v_rcp_f32_e32 v1, v1
	s_nop 0
	v_pk_mul_f32 v[0:1], v[6:7], v[0:1]
	s_nop 0
	v_pk_mul_f32 v[0:1], v[0:1], v[2:3]
	s_nop 0
	v_cvt_pk_bf16_f32 v11, v0, v1
	global_store_dwordx4 v[16:17], v[8:11], off
	s_cbranch_vccz .LBB0_111
	s_waitcnt vmcnt(0)
	v_readlane_b32 s22, v255, 14
	s_cmpk_gt_u32 s19, 0xff
	v_readlane_b32 s23, v255, 15
	s_mov_b64 s[28:29], s[54:55]
	s_cbranch_scc1 .LBB0_118
	s_barrier

; #define PG8_STAGE(bufoff, gbase, voff) do { _Pragma("unroll") for (int _i = 0; _i < 2; ++_i) \
;         __builtin_amdgcn_global_load_lds((const unsigned*)((const char*)(gbase) + (voff)[_i]), (PG8_LAS unsigned*)(lds + (bufoff) + ldsw + _i * 8192), 16, 0, 0); } while (0)
; #define PG8_LDA(dst, b, h) do { _Pragma("unroll") for (int m = 0; m < 4; ++m) _Pragma("unroll") for (int k = 0; k < 2; ++k) dst[m][k] = *(const PG8_LAS bf16x8*)(lds + PG8_SA(b, h) + aoff + m * 2048 + k * 1024); } while (0)
; #define PG8_LDB(dst, b, h) do { _Pragma("unroll") for (int n = 0; n < 2; ++n) _Pragma("unroll") for (int k = 0; k < 2; ++k) dst[n][k] = *(const PG8_LAS bf16x8*)(lds + PG8_SB(b, h) + boff + n * 2048 + k * 1024); } while (0)
; #define PG8_MMA(ai, bj, At, Bt) do { __builtin_amdgcn_s_setprio(1); _Pragma("unroll") for (int m = 0; m < 4; ++m) _Pragma("unroll") for (int n = 0; n < 2; ++n) _Pragma("unroll") for (int k = 0; k < 2; ++k) \
;         acc[ai][bj][m][n] = __builtin_amdgcn_mfma_f32_16x16x32_bf16(Bt[n][k], At[m][k], acc[ai][bj][m][n], 0, 0, 0); __builtin_amdgcn_s_setprio(0); } while (0)
; #define PG8_WAIT_V(n) asm volatile("s_waitcnt vmcnt(" #n ")" ::: "memory")
; template <class Epi, class Sched>
; __device__ __forceinline__ void gemm_phase(PG8_LAS unsigned char* lds, const Gemm g, const Sched& S, const Epi& E) {
;     ...
;         for (int t = 0; t < nt; t += 2) {
;             const bool last = (t == nt - 2);
;             const char* a1 = cA + (size_t)(t + 1) * kstep;
;             const char* a2 = last ? nA : cA + (size_t)(t + 2) * kstep; const char* b2 = last ? nB : cB + (size_t)(t + 2) * kstep;
;             const char* a3 = a2 + kstep; const char* b3 = b2 + kstep;
;             if (last && has_next) S.a_ready(nxt);
;             PG8_LDB(B0, 0, 0); PG8_SCHED; PG8_LDA(At, 0, 0); PG8_STAGE(PG8_SA(1, 1), a1 + hstep, voffA);
;             PG8_WAIT_L(8); PG8_BAR; PG8_WAIT_L(0); PG8_MMA(0, 0, At, B0); PG8_BAR; PG8_SCHED;
;             PG8_LDB(B1, 0, 1); PG8_STAGE(PG8_SB(0, 0), b2, voffB);
;             PG8_BAR; PG8_WAIT_L(0); PG8_MMA(0, 1, At, B1); PG8_BAR;
;             PG8_LDA(At, 0, 1); PG8_STAGE(PG8_SA(0, 0), a2, voffA);
;             PG8_BAR; PG8_WAIT_L(0); PG8_MMA(1, 0, At, B0); PG8_BAR; PG8_SCHED;
;             PG8_STAGE(PG8_SB(0, 1), b2 + hstep, voffB);
;             PG8_WAIT_V(6); PG8_BAR; PG8_MMA(1, 1, At, B1); PG8_BAR;
.LBB0_137:
	s_add_u32 s14, s12, 0xfffc0080
	s_addc_u32 s15, s13, -1
	s_add_i32 s46, 0, 0x10000
	v_add_u32_e32 v154, s46, v139
	ds_read_b128 v[142:145], v154
	ds_read_b128 v[146:149], v154 offset:1024
	ds_read_b128 v[150:153], v154 offset:2048
	ds_read_b128 v[154:157], v154 offset:3072
	s_cmp_eq_u32 s45, 12
	s_cselect_b32 s17, s7, s15
	s_cselect_b32 s16, s40, s14
	s_cselect_b32 s15, s5, s44
	s_cselect_b32 s14, s41, s43
	s_add_i32 m0, s1, 0xc000
	ds_read_b128 v[158:161], v141
	ds_read_b128 v[162:165], v141 offset:1024
	ds_read_b128 v[166:169], v141 offset:2048
	ds_read_b128 v[170:173], v141 offset:3072
	ds_read_b128 v[178:181], v141 offset:4096
	ds_read_b128 v[182:185], v141 offset:5120
	ds_read_b128 v[186:189], v141 offset:6144
	global_load_lds_dwordx4 v134, s[12:13]
	s_add_i32 m0, s1, 0xe000
	ds_read_b128 v[190:193], v141 offset:7168
	global_load_lds_dwordx4 v136, s[12:13]
	s_waitcnt lgkmcnt(8)
	s_barrier
	s_waitcnt lgkmcnt(0)
	s_setprio 1
	v_mfma_f32_16x16x32_bf16 v[124:127], v[142:145], v[158:161], v[124:127]
	v_mfma_f32_16x16x32_bf16 v[120:123], v[150:153], v[158:161], v[120:123]
	v_mfma_f32_16x16x32_bf16 v[116:119], v[142:145], v[166:169], v[116:119]
	v_mfma_f32_16x16x32_bf16 v[112:115], v[150:153], v[166:169], v[112:115]
	v_mfma_f32_16x16x32_bf16 v[100:103], v[142:145], v[178:181], v[100:103]
	v_mfma_f32_16x16x32_bf16 v[96:99], v[150:153], v[178:181], v[96:99]
	v_mfma_f32_16x16x32_bf16 v[84:87], v[142:145], v[186:189], v[84:87]
	v_mfma_f32_16x16x32_bf16 v[80:83], v[150:153], v[186:189], v[80:83]
	v_mfma_f32_16x16x32_bf16 v[124:127], v[146:149], v[162:165], v[124:127]
	v_mfma_f32_16x16x32_bf16 v[120:123], v[154:157], v[162:165], v[120:123]
	v_mfma_f32_16x16x32_bf16 v[116:119], v[146:149], v[170:173], v[116:119]
	v_mfma_f32_16x16x32_bf16 v[112:115], v[154:157], v[170:173], v[112:115]
	v_mfma_f32_16x16x32_bf16 v[100:103], v[146:149], v[182:185], v[100:103]
	v_mfma_f32_16x16x32_bf16 v[96:99], v[154:157], v[182:185], v[96:99]
	v_mfma_f32_16x16x32_bf16 v[84:87], v[146:149], v[190:193], v[84:87]
	v_mfma_f32_16x16x32_bf16 v[80:83], v[154:157], v[190:193], v[80:83]
	s_setprio 0
	s_barrier
	s_add_i32 s48, 0, 0x14000
	v_add_u32_e32 v174, s48, v139
	s_add_i32 s46, s46, s20
	ds_read_b128 v[194:197], v174
	ds_read_b128 v[198:201], v174 offset:1024
	ds_read_b128 v[202:205], v174 offset:2048
	s_add_u32 s98, s14, 0x80
	s_addc_u32 s99, s15, 0
	s_mov_b32 m0, s46
	ds_read_b128 v[206:209], v174 offset:3072
	global_load_lds_dwordx4 v176, s[14:15]
	s_add_i32 m0, s46, 0x2000
	s_nop 0
	global_load_lds_dwordx4 v128, s[14:15]
	s_barrier
	s_waitcnt lgkmcnt(0)
	s_setprio 1
	v_mfma_f32_16x16x32_bf16 v[108:111], v[194:197], v[158:161], v[108:111]
	v_mfma_f32_16x16x32_bf16 v[104:107], v[202:205], v[158:161], v[104:107]
	v_mfma_f32_16x16x32_bf16 v[92:95], v[194:197], v[166:169], v[92:95]
	v_mfma_f32_16x16x32_bf16 v[88:91], v[202:205], v[166:169], v[88:91]
	v_mfma_f32_16x16x32_bf16 v[76:79], v[194:197], v[178:181], v[76:79]
	v_mfma_f32_16x16x32_bf16 v[72:75], v[202:205], v[178:181], v[72:75]
	v_mfma_f32_16x16x32_bf16 v[68:71], v[194:197], v[186:189], v[68:71]
	v_mfma_f32_16x16x32_bf16 v[64:67], v[202:205], v[186:189], v[64:67]
	v_mfma_f32_16x16x32_bf16 v[108:111], v[198:201], v[162:165], v[108:111]
	v_mfma_f32_16x16x32_bf16 v[104:107], v[206:209], v[162:165], v[104:107]
	v_mfma_f32_16x16x32_bf16 v[92:95], v[198:201], v[170:173], v[92:95]
	v_mfma_f32_16x16x32_bf16 v[88:91], v[206:209], v[170:173], v[88:91]
	v_mfma_f32_16x16x32_bf16 v[76:79], v[198:201], v[182:185], v[76:79]
	v_mfma_f32_16x16x32_bf16 v[72:75], v[206:209], v[182:185], v[72:75]
	v_mfma_f32_16x16x32_bf16 v[68:71], v[198:201], v[190:193], v[68:71]
	v_mfma_f32_16x16x32_bf16 v[64:67], v[206:209], v[190:193], v[64:67]
	s_setprio 0
	s_mov_b32 m0, s1
	s_add_u32 s100, s16, 0x80
	s_addc_u32 s101, s17, 0
	s_barrier
	ds_read_b128 v[158:161], v141 offset:16384
	ds_read_b128 v[162:165], v141 offset:17408
	ds_read_b128 v[166:169], v141 offset:18432
	ds_read_b128 v[170:173], v141 offset:19456
	ds_read_b128 v[178:181], v141 offset:20480
	ds_read_b128 v[182:185], v141 offset:21504
	ds_read_b128 v[186:189], v141 offset:22528
	global_load_lds_dwordx4 v132, s[16:17]
	s_mov_b32 m0, s22
	ds_read_b128 v[190:193], v141 offset:23552
	global_load_lds_dwordx4 v130, s[16:17]
	s_barrier
	s_waitcnt lgkmcnt(0)
	s_setprio 1
	v_mfma_f32_16x16x32_bf16 v[60:63], v[142:145], v[158:161], v[60:63]
	v_mfma_f32_16x16x32_bf16 v[56:59], v[150:153], v[158:161], v[56:59]
	v_mfma_f32_16x16x32_bf16 v[52:55], v[142:145], v[166:169], v[52:55]
	v_mfma_f32_16x16x32_bf16 v[48:51], v[150:153], v[166:169], v[48:51]
	v_mfma_f32_16x16x32_bf16 v[36:39], v[142:145], v[178:181], v[36:39]
	v_mfma_f32_16x16x32_bf16 v[32:35], v[150:153], v[178:181], v[32:35]
	v_mfma_f32_16x16x32_bf16 v[20:23], v[142:145], v[186:189], v[20:23]
	v_mfma_f32_16x16x32_bf16 v[16:19], v[150:153], v[186:189], v[16:19]
	v_mfma_f32_16x16x32_bf16 v[60:63], v[146:149], v[162:165], v[60:63]
	v_mfma_f32_16x16x32_bf16 v[56:59], v[154:157], v[162:165], v[56:59]
	v_mfma_f32_16x16x32_bf16 v[52:55], v[146:149], v[170:173], v[52:55]
	v_mfma_f32_16x16x32_bf16 v[48:51], v[154:157], v[170:173], v[48:51]
	v_mfma_f32_16x16x32_bf16 v[36:39], v[146:149], v[182:185], v[36:39]
	v_mfma_f32_16x16x32_bf16 v[32:35], v[154:157], v[182:185], v[32:35]
	v_mfma_f32_16x16x32_bf16 v[20:23], v[146:149], v[190:193], v[20:23]
	v_mfma_f32_16x16x32_bf16 v[16:19], v[154:157], v[190:193], v[16:19]
	s_setprio 0
	s_barrier
	s_add_u32 s46, s14, 0x40000
	s_addc_u32 s47, s15, 0
	s_add_i32 s48, s48, s20
	s_mov_b32 m0, s48
	s_nop 0
	global_load_lds_dwordx4 v176, s[46:47]
	s_add_i32 m0, s48, 0x2000
	s_nop 0
	global_load_lds_dwordx4 v128, s[46:47]
	s_waitcnt vmcnt(6)
	s_barrier
; #define PG8_STAGE(bufoff, gbase, voff) do { _Pragma("unroll") for (int _i = 0; _i < 2; ++_i) \
;         __builtin_amdgcn_global_load_lds((const unsigned*)((const char*)(gbase) + (voff)[_i]), (PG8_LAS unsigned*)(lds + (bufoff) + ldsw + _i * 8192), 16, 0, 0); } while (0)
; #define PG8_LDA(dst, b, h) do { _Pragma("unroll") for (int m = 0; m < 4; ++m) _Pragma("unroll") for (int k = 0; k < 2; ++k) dst[m][k] = *(const PG8_LAS bf16x8*)(lds + PG8_SA(b, h) + aoff + m * 2048 + k * 1024); } while (0)
; #define PG8_LDB(dst, b, h) do { _Pragma("unroll") for (int n = 0; n < 2; ++n) _Pragma("unroll") for (int k = 0; k < 2; ++k) dst[n][k] = *(const PG8_LAS bf16x8*)(lds + PG8_SB(b, h) + boff + n * 2048 + k * 1024); } while (0)
; #define PG8_MMA(ai, bj, At, Bt) do { __builtin_amdgcn_s_setprio(1); _Pragma("unroll") for (int m = 0; m < 4; ++m) _Pragma("unroll") for (int n = 0; n < 2; ++n) _Pragma("unroll") for (int k = 0; k < 2; ++k) \
;         acc[ai][bj][m][n] = __builtin_amdgcn_mfma_f32_16x16x32_bf16(Bt[n][k], At[m][k], acc[ai][bj][m][n], 0, 0, 0); __builtin_amdgcn_s_setprio(0); } while (0)
; #define PG8_WAIT_V(n) asm volatile("s_waitcnt vmcnt(" #n ")" ::: "memory")
; #define PG8_WAIT_L(n) asm volatile("s_waitcnt lgkmcnt(" #n ")" ::: "memory")
; #define PG8_BAR __builtin_amdgcn_s_barrier()
; #define PG8_SCHED __builtin_amdgcn_sched_barrier(0)
; template <class Epi, class Sched>
; __device__ __forceinline__ void gemm_phase(PG8_LAS unsigned char* lds, const Gemm g, const Sched& S, const Epi& E) {
;     ...
;             PG8_WAIT_V(6); PG8_BAR; PG8_MMA(1, 1, At, B1); PG8_BAR;
;             PG8_LDB(B0, 1, 0); PG8_SCHED; PG8_LDA(At, 1, 0); PG8_STAGE(PG8_SA(0, 1), a2 + hstep, voffA);
;             PG8_WAIT_L(8); PG8_BAR; PG8_WAIT_L(0); PG8_MMA(0, 0, At, B0); PG8_BAR; PG8_SCHED;
;             PG8_LDB(B1, 1, 1); PG8_STAGE(PG8_SB(1, 0), b3, voffB);
;             PG8_BAR; PG8_WAIT_L(0); PG8_MMA(0, 1, At, B1); PG8_BAR;
;             PG8_LDA(At, 1, 1); PG8_STAGE(PG8_SA(1, 0), a3, voffA);
;             PG8_BAR; PG8_WAIT_L(0); PG8_MMA(1, 0, At, B0); PG8_BAR; PG8_SCHED;
	s_setprio 1
	v_mfma_f32_16x16x32_bf16 v[44:47], v[194:197], v[158:161], v[44:47]
	v_mfma_f32_16x16x32_bf16 v[40:43], v[202:205], v[158:161], v[40:43]
	v_mfma_f32_16x16x32_bf16 v[28:31], v[194:197], v[166:169], v[28:31]
	v_mfma_f32_16x16x32_bf16 v[24:27], v[202:205], v[166:169], v[24:27]
	v_mfma_f32_16x16x32_bf16 v[12:15], v[194:197], v[178:181], v[12:15]
	v_mfma_f32_16x16x32_bf16 v[8:11], v[202:205], v[178:181], v[8:11]
	v_mfma_f32_16x16x32_bf16 v[4:7], v[194:197], v[186:189], v[4:7]
	v_mfma_f32_16x16x32_bf16 v[0:3], v[202:205], v[186:189], v[0:3]
	v_mfma_f32_16x16x32_bf16 v[44:47], v[198:201], v[162:165], v[44:47]
	v_mfma_f32_16x16x32_bf16 v[40:43], v[206:209], v[162:165], v[40:43]
	v_mfma_f32_16x16x32_bf16 v[28:31], v[198:201], v[170:173], v[28:31]
	v_mfma_f32_16x16x32_bf16 v[24:27], v[206:209], v[170:173], v[24:27]
	v_mfma_f32_16x16x32_bf16 v[12:15], v[198:201], v[182:185], v[12:15]
	v_mfma_f32_16x16x32_bf16 v[8:11], v[206:209], v[182:185], v[8:11]
	v_mfma_f32_16x16x32_bf16 v[4:7], v[198:201], v[190:193], v[4:7]
	v_mfma_f32_16x16x32_bf16 v[0:3], v[206:209], v[190:193], v[0:3]
	s_setprio 0
	s_add_i32 s46, 0, 0x18000
	v_add_u32_e32 v154, s46, v139
	s_barrier
	ds_read_b128 v[142:145], v154
	ds_read_b128 v[146:149], v154 offset:1024
	ds_read_b128 v[150:153], v154 offset:2048
	ds_read_b128 v[154:157], v154 offset:3072
	s_add_u32 s16, s16, 0x40000
	s_addc_u32 s17, s17, 0
	s_mov_b32 m0, s23
	ds_read_b128 v[158:161], v141 offset:32768
	ds_read_b128 v[162:165], v141 offset:33792
	ds_read_b128 v[166:169], v141 offset:34816
	ds_read_b128 v[170:173], v141 offset:35840
	ds_read_b128 v[178:181], v141 offset:36864
	ds_read_b128 v[182:185], v141 offset:37888
	ds_read_b128 v[186:189], v141 offset:38912
	global_load_lds_dwordx4 v132, s[16:17]
	s_mov_b32 m0, s26
	ds_read_b128 v[190:193], v141 offset:39936
	global_load_lds_dwordx4 v130, s[16:17]
	s_waitcnt lgkmcnt(8)
	s_barrier
	s_waitcnt lgkmcnt(0)
	s_setprio 1
	v_mfma_f32_16x16x32_bf16 v[124:127], v[142:145], v[158:161], v[124:127]
	v_mfma_f32_16x16x32_bf16 v[120:123], v[150:153], v[158:161], v[120:123]
	v_mfma_f32_16x16x32_bf16 v[116:119], v[142:145], v[166:169], v[116:119]
	v_mfma_f32_16x16x32_bf16 v[112:115], v[150:153], v[166:169], v[112:115]
	v_mfma_f32_16x16x32_bf16 v[100:103], v[142:145], v[178:181], v[100:103]
	v_mfma_f32_16x16x32_bf16 v[96:99], v[150:153], v[178:181], v[96:99]
	v_mfma_f32_16x16x32_bf16 v[84:87], v[142:145], v[186:189], v[84:87]
	v_mfma_f32_16x16x32_bf16 v[80:83], v[150:153], v[186:189], v[80:83]
	v_mfma_f32_16x16x32_bf16 v[124:127], v[146:149], v[162:165], v[124:127]
	v_mfma_f32_16x16x32_bf16 v[120:123], v[154:157], v[162:165], v[120:123]
	v_mfma_f32_16x16x32_bf16 v[116:119], v[146:149], v[170:173], v[116:119]
	v_mfma_f32_16x16x32_bf16 v[112:115], v[154:157], v[170:173], v[112:115]
	v_mfma_f32_16x16x32_bf16 v[100:103], v[146:149], v[182:185], v[100:103]
	v_mfma_f32_16x16x32_bf16 v[96:99], v[154:157], v[182:185], v[96:99]
	v_mfma_f32_16x16x32_bf16 v[84:87], v[146:149], v[190:193], v[84:87]
	v_mfma_f32_16x16x32_bf16 v[80:83], v[154:157], v[190:193], v[80:83]
	s_setprio 0
	s_barrier
	s_add_i32 s16, 0, 0x1c000
	s_add_i32 s17, s46, s20
	v_add_u32_e32 v206, s16, v139
	s_mov_b32 m0, s17
	ds_read_b128 v[194:197], v206
	ds_read_b128 v[198:201], v206 offset:1024
	ds_read_b128 v[202:205], v206 offset:2048
	global_load_lds_dwordx4 v176, s[98:99]
	s_add_i32 m0, s17, 0x2000
	ds_read_b128 v[206:209], v206 offset:3072
	global_load_lds_dwordx4 v128, s[98:99]
	s_barrier
	s_waitcnt lgkmcnt(0)
	s_setprio 1
	v_mfma_f32_16x16x32_bf16 v[108:111], v[194:197], v[158:161], v[108:111]
	v_mfma_f32_16x16x32_bf16 v[104:107], v[202:205], v[158:161], v[104:107]
	v_mfma_f32_16x16x32_bf16 v[92:95], v[194:197], v[166:169], v[92:95]
	v_mfma_f32_16x16x32_bf16 v[88:91], v[202:205], v[166:169], v[88:91]
	v_mfma_f32_16x16x32_bf16 v[76:79], v[194:197], v[178:181], v[76:79]
	v_mfma_f32_16x16x32_bf16 v[72:75], v[202:205], v[178:181], v[72:75]
	v_mfma_f32_16x16x32_bf16 v[68:71], v[194:197], v[186:189], v[68:71]
	v_mfma_f32_16x16x32_bf16 v[64:67], v[202:205], v[186:189], v[64:67]
	v_mfma_f32_16x16x32_bf16 v[108:111], v[198:201], v[162:165], v[108:111]
	v_mfma_f32_16x16x32_bf16 v[104:107], v[206:209], v[162:165], v[104:107]
	v_mfma_f32_16x16x32_bf16 v[92:95], v[198:201], v[170:173], v[92:95]
	v_mfma_f32_16x16x32_bf16 v[88:91], v[206:209], v[170:173], v[88:91]
	v_mfma_f32_16x16x32_bf16 v[76:79], v[198:201], v[182:185], v[76:79]
	v_mfma_f32_16x16x32_bf16 v[72:75], v[206:209], v[182:185], v[72:75]
	v_mfma_f32_16x16x32_bf16 v[68:71], v[198:201], v[190:193], v[68:71]
	v_mfma_f32_16x16x32_bf16 v[64:67], v[206:209], v[190:193], v[64:67]
	s_setprio 0
	s_mov_b32 m0, s28
	s_barrier
	ds_read_b128 v[158:161], v141 offset:49152
	ds_read_b128 v[162:165], v141 offset:50176
	ds_read_b128 v[166:169], v141 offset:51200
	ds_read_b128 v[170:173], v141 offset:52224
	ds_read_b128 v[178:181], v141 offset:53248
	ds_read_b128 v[182:185], v141 offset:54272
	ds_read_b128 v[186:189], v141 offset:55296
	global_load_lds_dwordx4 v132, s[100:101]
	s_mov_b32 m0, s29
	ds_read_b128 v[190:193], v141 offset:56320
	global_load_lds_dwordx4 v130, s[100:101]
	s_barrier
; #define PG8_STAGE(bufoff, gbase, voff) do { _Pragma("unroll") for (int _i = 0; _i < 2; ++_i) \
;         __builtin_amdgcn_global_load_lds((const unsigned*)((const char*)(gbase) + (voff)[_i]), (PG8_LAS unsigned*)(lds + (bufoff) + ldsw + _i * 8192), 16, 0, 0); } while (0)
; #define PG8_MMA(ai, bj, At, Bt) do { __builtin_amdgcn_s_setprio(1); _Pragma("unroll") for (int m = 0; m < 4; ++m) _Pragma("unroll") for (int n = 0; n < 2; ++n) _Pragma("unroll") for (int k = 0; k < 2; ++k) \
;         acc[ai][bj][m][n] = __builtin_amdgcn_mfma_f32_16x16x32_bf16(Bt[n][k], At[m][k], acc[ai][bj][m][n], 0, 0, 0); __builtin_amdgcn_s_setprio(0); } while (0)
; #define PG8_WAIT_V(n) asm volatile("s_waitcnt vmcnt(" #n ")" ::: "memory")
; #define PG8_WAIT_L(n) asm volatile("s_waitcnt lgkmcnt(" #n ")" ::: "memory")
; #define PG8_BAR __builtin_amdgcn_s_barrier()
; #define PG8_SCHED __builtin_amdgcn_sched_barrier(0)
; template <class Epi, class Sched>
; __device__ __forceinline__ void gemm_phase(PG8_LAS unsigned char* lds, const Gemm g, const Sched& S, const Epi& E) {
;     ...
;             PG8_BAR; PG8_WAIT_L(0); PG8_MMA(1, 0, At, B0); PG8_BAR; PG8_SCHED;
;             PG8_STAGE(PG8_SB(1, 1), b3 + hstep, voffB);
;             PG8_WAIT_V(6); PG8_BAR; PG8_MMA(1, 1, At, B1); PG8_BAR;
;         }
	s_waitcnt lgkmcnt(0)
	s_setprio 1
	v_mfma_f32_16x16x32_bf16 v[60:63], v[142:145], v[158:161], v[60:63]
	v_mfma_f32_16x16x32_bf16 v[56:59], v[150:153], v[158:161], v[56:59]
	v_mfma_f32_16x16x32_bf16 v[52:55], v[142:145], v[166:169], v[52:55]
	v_mfma_f32_16x16x32_bf16 v[48:51], v[150:153], v[166:169], v[48:51]
	v_mfma_f32_16x16x32_bf16 v[36:39], v[142:145], v[178:181], v[36:39]
	v_mfma_f32_16x16x32_bf16 v[32:35], v[150:153], v[178:181], v[32:35]
	v_mfma_f32_16x16x32_bf16 v[20:23], v[142:145], v[186:189], v[20:23]
	v_mfma_f32_16x16x32_bf16 v[16:19], v[150:153], v[186:189], v[16:19]
	v_mfma_f32_16x16x32_bf16 v[60:63], v[146:149], v[162:165], v[60:63]
	v_mfma_f32_16x16x32_bf16 v[56:59], v[154:157], v[162:165], v[56:59]
	v_mfma_f32_16x16x32_bf16 v[52:55], v[146:149], v[170:173], v[52:55]
	v_mfma_f32_16x16x32_bf16 v[48:51], v[154:157], v[170:173], v[48:51]
	v_mfma_f32_16x16x32_bf16 v[36:39], v[146:149], v[182:185], v[36:39]
	v_mfma_f32_16x16x32_bf16 v[32:35], v[154:157], v[182:185], v[32:35]
	v_mfma_f32_16x16x32_bf16 v[20:23], v[146:149], v[190:193], v[20:23]
	v_mfma_f32_16x16x32_bf16 v[16:19], v[154:157], v[190:193], v[16:19]
	s_setprio 0
	s_barrier
	s_add_u32 s14, s14, 0x40080
	s_addc_u32 s15, s15, 0
	s_add_i32 s16, s16, s20
	s_mov_b32 m0, s16
	s_nop 0
	global_load_lds_dwordx4 v176, s[14:15]
	s_add_i32 m0, s16, 0x2000
	s_nop 0
	global_load_lds_dwordx4 v128, s[14:15]
	s_waitcnt vmcnt(6)
	s_barrier
	s_setprio 1
	v_mfma_f32_16x16x32_bf16 v[44:47], v[194:197], v[158:161], v[44:47]
	v_mfma_f32_16x16x32_bf16 v[40:43], v[202:205], v[158:161], v[40:43]
	v_mfma_f32_16x16x32_bf16 v[28:31], v[194:197], v[166:169], v[28:31]
	v_mfma_f32_16x16x32_bf16 v[24:27], v[202:205], v[166:169], v[24:27]
	v_mfma_f32_16x16x32_bf16 v[12:15], v[194:197], v[178:181], v[12:15]
	v_mfma_f32_16x16x32_bf16 v[8:11], v[202:205], v[178:181], v[8:11]
	v_mfma_f32_16x16x32_bf16 v[4:7], v[194:197], v[186:189], v[4:7]
	v_mfma_f32_16x16x32_bf16 v[0:3], v[202:205], v[186:189], v[0:3]
	v_mfma_f32_16x16x32_bf16 v[44:47], v[198:201], v[162:165], v[44:47]
	v_mfma_f32_16x16x32_bf16 v[40:43], v[206:209], v[162:165], v[40:43]
	v_mfma_f32_16x16x32_bf16 v[28:31], v[198:201], v[170:173], v[28:31]
	v_mfma_f32_16x16x32_bf16 v[24:27], v[206:209], v[170:173], v[24:27]
	v_mfma_f32_16x16x32_bf16 v[12:15], v[198:201], v[182:185], v[12:15]
	v_mfma_f32_16x16x32_bf16 v[8:11], v[206:209], v[182:185], v[8:11]
	v_mfma_f32_16x16x32_bf16 v[4:7], v[198:201], v[190:193], v[4:7]
	v_mfma_f32_16x16x32_bf16 v[0:3], v[206:209], v[190:193], v[0:3]
	s_setprio 0
	s_add_i32 s45, s45, 2
	s_add_u32 s12, s12, 0x100
	s_addc_u32 s13, s13, 0
	s_add_u32 s43, s43, 0x100
	s_addc_u32 s44, s44, 0
	s_cmp_gt_u32 s45, 13
	s_barrier
	s_cbranch_scc0 .LBB0_137
; __device__ __forceinline__ unsigned cvtpk(float lo, float hi) { const f32x2 v = (f32x2){lo, hi}; const bf16v2 b = __builtin_convertvector(v, bf16v2); return __builtin_bit_cast(unsigned, b); }
; #define PG8_WAIT_V(n) asm volatile("s_waitcnt vmcnt(" #n ")" ::: "memory")
; #define PG8_BAR __builtin_amdgcn_s_barrier()
; template <class Epi, class Sched>
; __device__ __forceinline__ void gemm_phase(PG8_LAS unsigned char* lds, const Gemm g, const Sched& S, const Epi& E) {
;     ...
;         if constexpr (!Epi::AFTER_DRAIN) { E(acc, cur, wr, wc, fr, fq); S.done(cur); }
;         if (!has_next) break;
; #pragma unroll
;         for (int a = 0; a < 2; ++a)
; #pragma unroll
;             for (int b = 0; b < 2; ++b)
; #pragma unroll
;                 for (int m = 0; m < 4; ++m)
; #pragma unroll
;                     for (int n = 0; n < 2; ++n) acc[a][b][m][n] = (f32x4){0.f, 0.f, 0.f, 0.f};
;         cur = nxt; cA = nA; cB = nB; ++ui;
;     }
;     PG8_WAIT_V(0);
;     if (wr == 0) PG8_BAR;
;     __device__ __forceinline__ void operator()(const f32x4 (&acc)[2][2][4][2], const pg8::Unit& u, int wr, int wc, int fr, int fq) const {
;         const int row0 = u.pm * 256 + wr * 64 + fr, col0 = u.pn * 256 + wc * 32 + 8 * fq;
; #pragma unroll
;         for (int ai = 0; ai < 2; ++ai)
; #pragma unroll
;             for (int m = 0; m < 4; ++m) { bf16_t* rowp = O + (size_t)(row0 + ai * 128 + m * 16) * ldc + col0;
; #pragma unroll
;                 for (int bj = 0; bj < 2; ++bj) { const f32x4 v0 = acc[ai][bj][m][0], v1 = acc[ai][bj][m][1];
;                     u32x4 w; w.x = cvtpk(v0[0], v0[1]); w.y = cvtpk(v0[2], v0[3]); w.z = cvtpk(v1[0], v1[1]); w.w = cvtpk(v1[2], v1[3]);
;                     *(u32x4*)(rowp + bj * 128) = w; } }
	v_lshl_add_u32 v142, s0, 8, v138
	v_lshl_or_b32 v144, s34, 8, v140
	v_ashrrev_i32_e32 v143, 31, v142
	v_readlane_b32 s12, v253, 18
	v_ashrrev_i32_e32 v145, 31, v144
	v_lshlrev_b64 v[146:147], 11, v[142:143]
	v_readlane_b32 s13, v253, 19
	v_cvt_pk_bf16_f32 v108, v108, v109
	v_cvt_pk_bf16_f32 v109, v110, v111
	v_cvt_pk_bf16_f32 v110, v104, v105
	v_or_b32_e32 v104, 16, v142
	v_cvt_pk_bf16_f32 v92, v92, v93
	v_cvt_pk_bf16_f32 v93, v94, v95
	v_cvt_pk_bf16_f32 v94, v88, v89
	v_or_b32_e32 v88, 32, v142
	v_cvt_pk_bf16_f32 v76, v76, v77
	v_cvt_pk_bf16_f32 v77, v78, v79
	v_cvt_pk_bf16_f32 v78, v72, v73
	v_or_b32_e32 v72, 48, v142
	v_lshl_add_u64 v[146:147], s[12:13], 0, v[146:147]
	v_lshlrev_b64 v[144:145], 1, v[144:145]
	v_ashrrev_i32_e32 v105, 31, v104
	v_ashrrev_i32_e32 v89, 31, v88
	v_ashrrev_i32_e32 v73, 31, v72
	v_lshl_add_u64 v[146:147], v[146:147], 0, v[144:145]
	v_lshlrev_b64 v[104:105], 11, v[104:105]
	v_lshlrev_b64 v[88:89], 11, v[88:89]
	v_lshlrev_b64 v[72:73], 11, v[72:73]
	v_lshl_add_u64 v[104:105], s[12:13], 0, v[104:105]
	v_lshl_add_u64 v[88:89], s[12:13], 0, v[88:89]
	v_lshl_add_u64 v[72:73], s[12:13], 0, v[72:73]
	s_mov_b64 s[12:13], 0x40000
	v_cvt_pk_bf16_f32 v60, v60, v61
	v_cvt_pk_bf16_f32 v61, v62, v63
	v_cvt_pk_bf16_f32 v62, v56, v57
	v_add_co_u32_e32 v56, vcc, s2, v146
	v_cvt_pk_bf16_f32 v68, v68, v69
	v_cvt_pk_bf16_f32 v69, v70, v71
	v_cvt_pk_bf16_f32 v70, v64, v65
	v_lshl_add_u64 v[64:65], v[146:147], 0, s[12:13]
	v_addc_co_u32_e32 v57, vcc, 0, v147, vcc
	v_cvt_pk_bf16_f32 v44, v44, v45
	v_cvt_pk_bf16_f32 v45, v46, v47
	v_cvt_pk_bf16_f32 v46, v40, v41
	v_cvt_pk_bf16_f32 v47, v42, v43
	s_mov_b32 s0, 0x48000
	global_store_dwordx4 v[64:65], v[44:47], off offset:256
	s_mov_b64 s[12:13], 0x48000
	v_cvt_pk_bf16_f32 v28, v28, v29
	v_add_co_u32_e32 v46, vcc, s0, v146
	v_lshl_add_u64 v[44:45], v[146:147], 0, s[12:13]
	s_nop 0
	v_addc_co_u32_e32 v47, vcc, 0, v147, vcc
	v_cvt_pk_bf16_f32 v29, v30, v31
	v_cvt_pk_bf16_f32 v30, v24, v25
	v_cvt_pk_bf16_f32 v31, v26, v27
	s_mov_b32 s0, 0x50000
	global_store_dwordx4 v[44:45], v[28:31], off offset:256
	s_mov_b64 s[12:13], 0x50000
	v_cvt_pk_bf16_f32 v111, v106, v107
	v_add_co_u32_e32 v30, vcc, s0, v146
	v_lshl_add_u64 v[28:29], v[146:147], 0, s[12:13]
	s_nop 0
	v_addc_co_u32_e32 v31, vcc, 0, v147, vcc
	v_cvt_pk_bf16_f32 v12, v12, v13
	v_cvt_pk_bf16_f32 v13, v14, v15
	v_cvt_pk_bf16_f32 v14, v8, v9
	v_cvt_pk_bf16_f32 v15, v10, v11
	s_mov_b32 s0, 0x58000
	global_store_dwordx4 v[146:147], v[108:111], off offset:256
	v_cvt_pk_bf16_f32 v95, v90, v91
	global_store_dwordx4 v[28:29], v[12:15], off offset:256
	v_lshl_add_u64 v[108:109], v[104:105], 0, v[144:145]
	global_store_dwordx4 v[108:109], v[92:95], off offset:256
	v_add_co_u32_e32 v14, vcc, s0, v146
	s_nop 0
	v_lshl_add_u64 v[92:93], v[88:89], 0, v[144:145]
	v_cvt_pk_bf16_f32 v79, v74, v75
	s_mov_b64 s[12:13], 0x58000
	v_addc_co_u32_e32 v15, vcc, 0, v147, vcc
	v_cvt_pk_bf16_f32 v124, v124, v125
	v_cvt_pk_bf16_f32 v125, v126, v127
	v_cvt_pk_bf16_f32 v126, v120, v121
	v_cvt_pk_bf16_f32 v127, v122, v123
	v_cvt_pk_bf16_f32 v104, v116, v117
	v_cvt_pk_bf16_f32 v105, v118, v119
	v_cvt_pk_bf16_f32 v106, v112, v113
	v_cvt_pk_bf16_f32 v107, v114, v115
	v_cvt_pk_bf16_f32 v88, v100, v101
	v_cvt_pk_bf16_f32 v89, v102, v103
	v_cvt_pk_bf16_f32 v90, v96, v97
	v_cvt_pk_bf16_f32 v91, v98, v99
	global_store_dwordx4 v[92:93], v[76:79], off offset:256
	v_cvt_pk_bf16_f32 v74, v80, v81
	v_cvt_pk_bf16_f32 v75, v82, v83
	v_lshl_add_u64 v[76:77], v[72:73], 0, v[144:145]
	v_cvt_pk_bf16_f32 v72, v84, v85
	v_cvt_pk_bf16_f32 v73, v86, v87
	v_cvt_pk_bf16_f32 v71, v66, v67
	v_cvt_pk_bf16_f32 v63, v58, v59
	v_cvt_pk_bf16_f32 v40, v52, v53
	v_cvt_pk_bf16_f32 v41, v54, v55
	v_cvt_pk_bf16_f32 v42, v48, v49
	v_cvt_pk_bf16_f32 v43, v50, v51
	v_cvt_pk_bf16_f32 v24, v36, v37
	v_cvt_pk_bf16_f32 v25, v38, v39
	v_cvt_pk_bf16_f32 v26, v32, v33
	v_cvt_pk_bf16_f32 v27, v34, v35
	v_lshl_add_u64 v[12:13], v[146:147], 0, s[12:13]
	v_cvt_pk_bf16_f32 v8, v20, v21
	v_cvt_pk_bf16_f32 v9, v22, v23
	v_cvt_pk_bf16_f32 v10, v16, v17
	v_cvt_pk_bf16_f32 v11, v18, v19
	v_cvt_pk_bf16_f32 v4, v4, v5
	v_cvt_pk_bf16_f32 v5, v6, v7
	v_cvt_pk_bf16_f32 v6, v0, v1
	v_cvt_pk_bf16_f32 v7, v2, v3
	s_and_b64 vcc, exec, s[38:39]
	s_mov_b32 s34, s4
	s_mov_b32 s0, s6
	s_mov_b64 s[14:15], s[10:11]
	s_mov_b64 s[12:13], s[8:9]
	global_store_dwordx4 v[146:147], v[124:127], off
	global_store_dwordx4 v[108:109], v[104:107], off
	global_store_dwordx4 v[92:93], v[88:91], off
	global_store_dwordx4 v[76:77], v[72:75], off
	global_store_dwordx4 v[76:77], v[68:71], off offset:256
	global_store_dwordx4 v[56:57], v[60:63], off
	global_store_dwordx4 v[46:47], v[40:43], off
	global_store_dwordx4 v[30:31], v[24:27], off
	global_store_dwordx4 v[14:15], v[8:11], off
	global_store_dwordx4 v[12:13], v[4:7], off offset:256
	s_cbranch_vccz .LBB0_134
	s_waitcnt vmcnt(0)
	v_readlane_b32 s22, v255, 14
	s_cmpk_gt_u32 s19, 0xff
	v_readlane_b32 s23, v255, 15
	s_mov_b64 s[28:29], s[54:55]
	s_cbranch_scc1 .LBB0_141
	s_barrier

; #define PG8_STAGE(bufoff, gbase, voff) do { _Pragma("unroll") for (int _i = 0; _i < 2; ++_i) \
;         __builtin_amdgcn_global_load_lds((const unsigned*)((const char*)(gbase) + (voff)[_i]), (PG8_LAS unsigned*)(lds + (bufoff) + ldsw + _i * 8192), 16, 0, 0); } while (0)
; #define PG8_LDA(dst, b, h) do { _Pragma("unroll") for (int m = 0; m < 4; ++m) _Pragma("unroll") for (int k = 0; k < 2; ++k) dst[m][k] = *(const PG8_LAS bf16x8*)(lds + PG8_SA(b, h) + aoff + m * 2048 + k * 1024); } while (0)
; #define PG8_LDB(dst, b, h) do { _Pragma("unroll") for (int n = 0; n < 2; ++n) _Pragma("unroll") for (int k = 0; k < 2; ++k) dst[n][k] = *(const PG8_LAS bf16x8*)(lds + PG8_SB(b, h) + boff + n * 2048 + k * 1024); } while (0)
; #define PG8_MMA(ai, bj, At, Bt) do { __builtin_amdgcn_s_setprio(1); _Pragma("unroll") for (int m = 0; m < 4; ++m) _Pragma("unroll") for (int n = 0; n < 2; ++n) _Pragma("unroll") for (int k = 0; k < 2; ++k) \
;         acc[ai][bj][m][n] = __builtin_amdgcn_mfma_f32_16x16x32_bf16(Bt[n][k], At[m][k], acc[ai][bj][m][n], 0, 0, 0); __builtin_amdgcn_s_setprio(0); } while (0)
; #define PG8_WAIT_V(n) asm volatile("s_waitcnt vmcnt(" #n ")" ::: "memory")
; template <class Epi, class Sched>
; __device__ __forceinline__ void gemm_phase(PG8_LAS unsigned char* lds, const Gemm g, const Sched& S, const Epi& E) {
;     ...
;         for (int t = 0; t < nt; t += 2) {
;             const bool last = (t == nt - 2);
;             const char* a1 = cA + (size_t)(t + 1) * kstep;
;             const char* a2 = last ? nA : cA + (size_t)(t + 2) * kstep; const char* b2 = last ? nB : cB + (size_t)(t + 2) * kstep;
;             const char* a3 = a2 + kstep; const char* b3 = b2 + kstep;
;             if (last && has_next) S.a_ready(nxt);
;             PG8_LDB(B0, 0, 0); PG8_SCHED; PG8_LDA(At, 0, 0); PG8_STAGE(PG8_SA(1, 1), a1 + hstep, voffA);
;             PG8_WAIT_L(8); PG8_BAR; PG8_WAIT_L(0); PG8_MMA(0, 0, At, B0); PG8_BAR; PG8_SCHED;
;             PG8_LDB(B1, 0, 1); PG8_STAGE(PG8_SB(0, 0), b2, voffB);
;             PG8_BAR; PG8_WAIT_L(0); PG8_MMA(0, 1, At, B1); PG8_BAR;
;             PG8_LDA(At, 0, 1); PG8_STAGE(PG8_SA(0, 0), a2, voffA);
;             PG8_BAR; PG8_WAIT_L(0); PG8_MMA(1, 0, At, B0); PG8_BAR; PG8_SCHED;
;             PG8_STAGE(PG8_SB(0, 1), b2 + hstep, voffB);
;             PG8_WAIT_V(6); PG8_BAR; PG8_MMA(1, 1, At, B1); PG8_BAR;
.LBB0_358:
	s_add_u32 s14, s12, 0xfffc0080
	s_addc_u32 s15, s13, -1
	s_add_i32 s46, 0, 0x10000
	v_add_u32_e32 v154, s46, v139
	ds_read_b128 v[142:145], v154
	ds_read_b128 v[146:149], v154 offset:1024
	ds_read_b128 v[150:153], v154 offset:2048
	ds_read_b128 v[154:157], v154 offset:3072
	s_cmp_eq_u32 s45, 12
	s_cselect_b32 s17, s7, s15
	s_cselect_b32 s16, s40, s14
	s_cselect_b32 s15, s5, s44
	s_cselect_b32 s14, s41, s43
	s_add_i32 m0, s1, 0xc000
	ds_read_b128 v[158:161], v141
	ds_read_b128 v[162:165], v141 offset:1024
	ds_read_b128 v[166:169], v141 offset:2048
	ds_read_b128 v[170:173], v141 offset:3072
	ds_read_b128 v[182:185], v141 offset:4096
	ds_read_b128 v[190:193], v141 offset:5120
	ds_read_b128 v[194:197], v141 offset:6144
	global_load_lds_dwordx4 v134, s[12:13]
	s_add_i32 m0, s1, 0xe000
	ds_read_b128 v[198:201], v141 offset:7168
	global_load_lds_dwordx4 v136, s[12:13]
	s_waitcnt lgkmcnt(8)
	s_barrier
	s_waitcnt lgkmcnt(0)
	s_setprio 1
	v_mfma_f32_16x16x32_bf16 v[124:127], v[142:145], v[158:161], v[124:127]
	v_mfma_f32_16x16x32_bf16 v[120:123], v[150:153], v[158:161], v[120:123]
	v_mfma_f32_16x16x32_bf16 v[116:119], v[142:145], v[166:169], v[116:119]
	v_mfma_f32_16x16x32_bf16 v[112:115], v[150:153], v[166:169], v[112:115]
	v_mfma_f32_16x16x32_bf16 v[100:103], v[142:145], v[182:185], v[100:103]
	v_mfma_f32_16x16x32_bf16 v[96:99], v[150:153], v[182:185], v[96:99]
	v_mfma_f32_16x16x32_bf16 v[84:87], v[142:145], v[194:197], v[84:87]
	v_mfma_f32_16x16x32_bf16 v[80:83], v[150:153], v[194:197], v[80:83]
	v_mfma_f32_16x16x32_bf16 v[124:127], v[146:149], v[162:165], v[124:127]
	v_mfma_f32_16x16x32_bf16 v[120:123], v[154:157], v[162:165], v[120:123]
	v_mfma_f32_16x16x32_bf16 v[116:119], v[146:149], v[170:173], v[116:119]
	v_mfma_f32_16x16x32_bf16 v[112:115], v[154:157], v[170:173], v[112:115]
	v_mfma_f32_16x16x32_bf16 v[100:103], v[146:149], v[190:193], v[100:103]
	v_mfma_f32_16x16x32_bf16 v[96:99], v[154:157], v[190:193], v[96:99]
	v_mfma_f32_16x16x32_bf16 v[84:87], v[146:149], v[198:201], v[84:87]
	v_mfma_f32_16x16x32_bf16 v[80:83], v[154:157], v[198:201], v[80:83]
	s_setprio 0
	s_barrier
	s_add_i32 s48, 0, 0x14000
	v_add_u32_e32 v174, s48, v139
	s_add_i32 s46, s46, s20
	ds_read_b128 v[202:205], v174
	ds_read_b128 v[206:209], v174 offset:1024
	ds_read_b128 v[210:213], v174 offset:2048
	s_add_u32 s98, s14, 0x80
	s_addc_u32 s99, s15, 0
	s_mov_b32 m0, s46
	ds_read_b128 v[214:217], v174 offset:3072
	global_load_lds_dwordx4 v176, s[14:15]
	s_add_i32 m0, s46, 0x2000
	s_nop 0
	global_load_lds_dwordx4 v128, s[14:15]
	s_barrier
	s_waitcnt lgkmcnt(0)
	s_setprio 1
	v_mfma_f32_16x16x32_bf16 v[108:111], v[202:205], v[158:161], v[108:111]
	v_mfma_f32_16x16x32_bf16 v[104:107], v[210:213], v[158:161], v[104:107]
	v_mfma_f32_16x16x32_bf16 v[92:95], v[202:205], v[166:169], v[92:95]
	v_mfma_f32_16x16x32_bf16 v[88:91], v[210:213], v[166:169], v[88:91]
	v_mfma_f32_16x16x32_bf16 v[76:79], v[202:205], v[182:185], v[76:79]
	v_mfma_f32_16x16x32_bf16 v[72:75], v[210:213], v[182:185], v[72:75]
	v_mfma_f32_16x16x32_bf16 v[68:71], v[202:205], v[194:197], v[68:71]
	v_mfma_f32_16x16x32_bf16 v[64:67], v[210:213], v[194:197], v[64:67]
	v_mfma_f32_16x16x32_bf16 v[108:111], v[206:209], v[162:165], v[108:111]
	v_mfma_f32_16x16x32_bf16 v[104:107], v[214:217], v[162:165], v[104:107]
	v_mfma_f32_16x16x32_bf16 v[92:95], v[206:209], v[170:173], v[92:95]
	v_mfma_f32_16x16x32_bf16 v[88:91], v[214:217], v[170:173], v[88:91]
	v_mfma_f32_16x16x32_bf16 v[76:79], v[206:209], v[190:193], v[76:79]
	v_mfma_f32_16x16x32_bf16 v[72:75], v[214:217], v[190:193], v[72:75]
	v_mfma_f32_16x16x32_bf16 v[68:71], v[206:209], v[198:201], v[68:71]
	v_mfma_f32_16x16x32_bf16 v[64:67], v[214:217], v[198:201], v[64:67]
	s_setprio 0
	s_mov_b32 m0, s1
	s_add_u32 s100, s16, 0x80
	s_addc_u32 s101, s17, 0
	s_barrier
	ds_read_b128 v[158:161], v141 offset:16384
	ds_read_b128 v[162:165], v141 offset:17408
	ds_read_b128 v[166:169], v141 offset:18432
	ds_read_b128 v[170:173], v141 offset:19456
	ds_read_b128 v[182:185], v141 offset:20480
	ds_read_b128 v[190:193], v141 offset:21504
	ds_read_b128 v[194:197], v141 offset:22528
	global_load_lds_dwordx4 v132, s[16:17]
	s_mov_b32 m0, s22
	ds_read_b128 v[198:201], v141 offset:23552
	global_load_lds_dwordx4 v130, s[16:17]
	s_barrier
	s_waitcnt lgkmcnt(0)
	s_setprio 1
	v_mfma_f32_16x16x32_bf16 v[60:63], v[142:145], v[158:161], v[60:63]
	v_mfma_f32_16x16x32_bf16 v[56:59], v[150:153], v[158:161], v[56:59]
	v_mfma_f32_16x16x32_bf16 v[52:55], v[142:145], v[166:169], v[52:55]
	v_mfma_f32_16x16x32_bf16 v[48:51], v[150:153], v[166:169], v[48:51]
	v_mfma_f32_16x16x32_bf16 v[36:39], v[142:145], v[182:185], v[36:39]
	v_mfma_f32_16x16x32_bf16 v[32:35], v[150:153], v[182:185], v[32:35]
	v_mfma_f32_16x16x32_bf16 v[20:23], v[142:145], v[194:197], v[20:23]
	v_mfma_f32_16x16x32_bf16 v[16:19], v[150:153], v[194:197], v[16:19]
	v_mfma_f32_16x16x32_bf16 v[60:63], v[146:149], v[162:165], v[60:63]
	v_mfma_f32_16x16x32_bf16 v[56:59], v[154:157], v[162:165], v[56:59]
	v_mfma_f32_16x16x32_bf16 v[52:55], v[146:149], v[170:173], v[52:55]
	v_mfma_f32_16x16x32_bf16 v[48:51], v[154:157], v[170:173], v[48:51]
	v_mfma_f32_16x16x32_bf16 v[36:39], v[146:149], v[190:193], v[36:39]
	v_mfma_f32_16x16x32_bf16 v[32:35], v[154:157], v[190:193], v[32:35]
	v_mfma_f32_16x16x32_bf16 v[20:23], v[146:149], v[198:201], v[20:23]
	v_mfma_f32_16x16x32_bf16 v[16:19], v[154:157], v[198:201], v[16:19]
	s_setprio 0
	s_barrier
	s_add_u32 s46, s14, 0x40000
	s_addc_u32 s47, s15, 0
	s_add_i32 s48, s48, s20
	s_mov_b32 m0, s48
	s_nop 0
	global_load_lds_dwordx4 v176, s[46:47]
	s_add_i32 m0, s48, 0x2000
	s_nop 0
	global_load_lds_dwordx4 v128, s[46:47]
	s_waitcnt vmcnt(6)
	s_barrier
; #define PG8_STAGE(bufoff, gbase, voff) do { _Pragma("unroll") for (int _i = 0; _i < 2; ++_i) \
;         __builtin_amdgcn_global_load_lds((const unsigned*)((const char*)(gbase) + (voff)[_i]), (PG8_LAS unsigned*)(lds + (bufoff) + ldsw + _i * 8192), 16, 0, 0); } while (0)
; #define PG8_LDA(dst, b, h) do { _Pragma("unroll") for (int m = 0; m < 4; ++m) _Pragma("unroll") for (int k = 0; k < 2; ++k) dst[m][k] = *(const PG8_LAS bf16x8*)(lds + PG8_SA(b, h) + aoff + m * 2048 + k * 1024); } while (0)
; #define PG8_LDB(dst, b, h) do { _Pragma("unroll") for (int n = 0; n < 2; ++n) _Pragma("unroll") for (int k = 0; k < 2; ++k) dst[n][k] = *(const PG8_LAS bf16x8*)(lds + PG8_SB(b, h) + boff + n * 2048 + k * 1024); } while (0)
; #define PG8_MMA(ai, bj, At, Bt) do { __builtin_amdgcn_s_setprio(1); _Pragma("unroll") for (int m = 0; m < 4; ++m) _Pragma("unroll") for (int n = 0; n < 2; ++n) _Pragma("unroll") for (int k = 0; k < 2; ++k) \
;         acc[ai][bj][m][n] = __builtin_amdgcn_mfma_f32_16x16x32_bf16(Bt[n][k], At[m][k], acc[ai][bj][m][n], 0, 0, 0); __builtin_amdgcn_s_setprio(0); } while (0)
; #define PG8_WAIT_V(n) asm volatile("s_waitcnt vmcnt(" #n ")" ::: "memory")
; #define PG8_WAIT_L(n) asm volatile("s_waitcnt lgkmcnt(" #n ")" ::: "memory")
; #define PG8_BAR __builtin_amdgcn_s_barrier()
; #define PG8_SCHED __builtin_amdgcn_sched_barrier(0)
; template <class Epi, class Sched>
; __device__ __forceinline__ void gemm_phase(PG8_LAS unsigned char* lds, const Gemm g, const Sched& S, const Epi& E) {
;     ...
;             PG8_WAIT_V(6); PG8_BAR; PG8_MMA(1, 1, At, B1); PG8_BAR;
;             PG8_LDB(B0, 1, 0); PG8_SCHED; PG8_LDA(At, 1, 0); PG8_STAGE(PG8_SA(0, 1), a2 + hstep, voffA);
;             PG8_WAIT_L(8); PG8_BAR; PG8_WAIT_L(0); PG8_MMA(0, 0, At, B0); PG8_BAR; PG8_SCHED;
;             PG8_LDB(B1, 1, 1); PG8_STAGE(PG8_SB(1, 0), b3, voffB);
;             PG8_BAR; PG8_WAIT_L(0); PG8_MMA(0, 1, At, B1); PG8_BAR;
;             PG8_LDA(At, 1, 1); PG8_STAGE(PG8_SA(1, 0), a3, voffA);
;             PG8_BAR; PG8_WAIT_L(0); PG8_MMA(1, 0, At, B0); PG8_BAR; PG8_SCHED;
	s_setprio 1
	v_mfma_f32_16x16x32_bf16 v[44:47], v[202:205], v[158:161], v[44:47]
	v_mfma_f32_16x16x32_bf16 v[40:43], v[210:213], v[158:161], v[40:43]
	v_mfma_f32_16x16x32_bf16 v[28:31], v[202:205], v[166:169], v[28:31]
	v_mfma_f32_16x16x32_bf16 v[24:27], v[210:213], v[166:169], v[24:27]
	v_mfma_f32_16x16x32_bf16 v[12:15], v[202:205], v[182:185], v[12:15]
	v_mfma_f32_16x16x32_bf16 v[8:11], v[210:213], v[182:185], v[8:11]
	v_mfma_f32_16x16x32_bf16 v[4:7], v[202:205], v[194:197], v[4:7]
	v_mfma_f32_16x16x32_bf16 v[0:3], v[210:213], v[194:197], v[0:3]
	v_mfma_f32_16x16x32_bf16 v[44:47], v[206:209], v[162:165], v[44:47]
	v_mfma_f32_16x16x32_bf16 v[40:43], v[214:217], v[162:165], v[40:43]
	v_mfma_f32_16x16x32_bf16 v[28:31], v[206:209], v[170:173], v[28:31]
	v_mfma_f32_16x16x32_bf16 v[24:27], v[214:217], v[170:173], v[24:27]
	v_mfma_f32_16x16x32_bf16 v[12:15], v[206:209], v[190:193], v[12:15]
	v_mfma_f32_16x16x32_bf16 v[8:11], v[214:217], v[190:193], v[8:11]
	v_mfma_f32_16x16x32_bf16 v[4:7], v[206:209], v[198:201], v[4:7]
	v_mfma_f32_16x16x32_bf16 v[0:3], v[214:217], v[198:201], v[0:3]
	s_setprio 0
	s_add_i32 s46, 0, 0x18000
	v_add_u32_e32 v154, s46, v139
	s_barrier
	ds_read_b128 v[142:145], v154
	ds_read_b128 v[146:149], v154 offset:1024
	ds_read_b128 v[150:153], v154 offset:2048
	ds_read_b128 v[154:157], v154 offset:3072
	s_add_u32 s16, s16, 0x40000
	s_addc_u32 s17, s17, 0
	s_mov_b32 m0, s23
	ds_read_b128 v[158:161], v141 offset:32768
	ds_read_b128 v[162:165], v141 offset:33792
	ds_read_b128 v[166:169], v141 offset:34816
	ds_read_b128 v[170:173], v141 offset:35840
	ds_read_b128 v[182:185], v141 offset:36864
	ds_read_b128 v[190:193], v141 offset:37888
	ds_read_b128 v[194:197], v141 offset:38912
	global_load_lds_dwordx4 v132, s[16:17]
	s_mov_b32 m0, s26
	ds_read_b128 v[198:201], v141 offset:39936
	global_load_lds_dwordx4 v130, s[16:17]
	s_waitcnt lgkmcnt(8)
	s_barrier
	s_waitcnt lgkmcnt(0)
	s_setprio 1
	v_mfma_f32_16x16x32_bf16 v[124:127], v[142:145], v[158:161], v[124:127]
	v_mfma_f32_16x16x32_bf16 v[120:123], v[150:153], v[158:161], v[120:123]
	v_mfma_f32_16x16x32_bf16 v[116:119], v[142:145], v[166:169], v[116:119]
	v_mfma_f32_16x16x32_bf16 v[112:115], v[150:153], v[166:169], v[112:115]
	v_mfma_f32_16x16x32_bf16 v[100:103], v[142:145], v[182:185], v[100:103]
	v_mfma_f32_16x16x32_bf16 v[96:99], v[150:153], v[182:185], v[96:99]
	v_mfma_f32_16x16x32_bf16 v[84:87], v[142:145], v[194:197], v[84:87]
	v_mfma_f32_16x16x32_bf16 v[80:83], v[150:153], v[194:197], v[80:83]
	v_mfma_f32_16x16x32_bf16 v[124:127], v[146:149], v[162:165], v[124:127]
	v_mfma_f32_16x16x32_bf16 v[120:123], v[154:157], v[162:165], v[120:123]
	v_mfma_f32_16x16x32_bf16 v[116:119], v[146:149], v[170:173], v[116:119]
	v_mfma_f32_16x16x32_bf16 v[112:115], v[154:157], v[170:173], v[112:115]
	v_mfma_f32_16x16x32_bf16 v[100:103], v[146:149], v[190:193], v[100:103]
	v_mfma_f32_16x16x32_bf16 v[96:99], v[154:157], v[190:193], v[96:99]
	v_mfma_f32_16x16x32_bf16 v[84:87], v[146:149], v[198:201], v[84:87]
	v_mfma_f32_16x16x32_bf16 v[80:83], v[154:157], v[198:201], v[80:83]
	s_setprio 0
	s_barrier
	s_add_i32 s16, 0, 0x1c000
	s_add_i32 s17, s46, s20
	v_add_u32_e32 v188, s16, v139
	s_mov_b32 m0, s17
	ds_read_b128 v[202:205], v188
	ds_read_b128 v[206:209], v188 offset:1024
	ds_read_b128 v[210:213], v188 offset:2048
	global_load_lds_dwordx4 v176, s[98:99]
	s_add_i32 m0, s17, 0x2000
	ds_read_b128 v[214:217], v188 offset:3072
	global_load_lds_dwordx4 v128, s[98:99]
	s_barrier
	s_waitcnt lgkmcnt(0)
	s_setprio 1
	v_mfma_f32_16x16x32_bf16 v[108:111], v[202:205], v[158:161], v[108:111]
	v_mfma_f32_16x16x32_bf16 v[104:107], v[210:213], v[158:161], v[104:107]
	v_mfma_f32_16x16x32_bf16 v[92:95], v[202:205], v[166:169], v[92:95]
	v_mfma_f32_16x16x32_bf16 v[88:91], v[210:213], v[166:169], v[88:91]
	v_mfma_f32_16x16x32_bf16 v[76:79], v[202:205], v[182:185], v[76:79]
	v_mfma_f32_16x16x32_bf16 v[72:75], v[210:213], v[182:185], v[72:75]
	v_mfma_f32_16x16x32_bf16 v[68:71], v[202:205], v[194:197], v[68:71]
	v_mfma_f32_16x16x32_bf16 v[64:67], v[210:213], v[194:197], v[64:67]
	v_mfma_f32_16x16x32_bf16 v[108:111], v[206:209], v[162:165], v[108:111]
	v_mfma_f32_16x16x32_bf16 v[104:107], v[214:217], v[162:165], v[104:107]
	v_mfma_f32_16x16x32_bf16 v[92:95], v[206:209], v[170:173], v[92:95]
	v_mfma_f32_16x16x32_bf16 v[88:91], v[214:217], v[170:173], v[88:91]
	v_mfma_f32_16x16x32_bf16 v[76:79], v[206:209], v[190:193], v[76:79]
	v_mfma_f32_16x16x32_bf16 v[72:75], v[214:217], v[190:193], v[72:75]
	v_mfma_f32_16x16x32_bf16 v[68:71], v[206:209], v[198:201], v[68:71]
	v_mfma_f32_16x16x32_bf16 v[64:67], v[214:217], v[198:201], v[64:67]
	s_setprio 0
	s_mov_b32 m0, s28
	s_barrier
	ds_read_b128 v[158:161], v141 offset:49152
	ds_read_b128 v[162:165], v141 offset:50176
	ds_read_b128 v[166:169], v141 offset:51200
	ds_read_b128 v[170:173], v141 offset:52224
	ds_read_b128 v[182:185], v141 offset:53248
	ds_read_b128 v[190:193], v141 offset:54272
	ds_read_b128 v[194:197], v141 offset:55296
	global_load_lds_dwordx4 v132, s[100:101]
	s_mov_b32 m0, s29
	ds_read_b128 v[198:201], v141 offset:56320
	global_load_lds_dwordx4 v130, s[100:101]
	s_barrier
; #define PG8_STAGE(bufoff, gbase, voff) do { _Pragma("unroll") for (int _i = 0; _i < 2; ++_i) \
;         __builtin_amdgcn_global_load_lds((const unsigned*)((const char*)(gbase) + (voff)[_i]), (PG8_LAS unsigned*)(lds + (bufoff) + ldsw + _i * 8192), 16, 0, 0); } while (0)
; #define PG8_MMA(ai, bj, At, Bt) do { __builtin_amdgcn_s_setprio(1); _Pragma("unroll") for (int m = 0; m < 4; ++m) _Pragma("unroll") for (int n = 0; n < 2; ++n) _Pragma("unroll") for (int k = 0; k < 2; ++k) \
;         acc[ai][bj][m][n] = __builtin_amdgcn_mfma_f32_16x16x32_bf16(Bt[n][k], At[m][k], acc[ai][bj][m][n], 0, 0, 0); __builtin_amdgcn_s_setprio(0); } while (0)
; #define PG8_WAIT_V(n) asm volatile("s_waitcnt vmcnt(" #n ")" ::: "memory")
; #define PG8_WAIT_L(n) asm volatile("s_waitcnt lgkmcnt(" #n ")" ::: "memory")
; #define PG8_BAR __builtin_amdgcn_s_barrier()
; #define PG8_SCHED __builtin_amdgcn_sched_barrier(0)
; template <class Epi, class Sched>
; __device__ __forceinline__ void gemm_phase(PG8_LAS unsigned char* lds, const Gemm g, const Sched& S, const Epi& E) {
;     ...
;             PG8_BAR; PG8_WAIT_L(0); PG8_MMA(1, 0, At, B0); PG8_BAR; PG8_SCHED;
;             PG8_STAGE(PG8_SB(1, 1), b3 + hstep, voffB);
;             PG8_WAIT_V(6); PG8_BAR; PG8_MMA(1, 1, At, B1); PG8_BAR;
;         }
	s_waitcnt lgkmcnt(0)
	s_setprio 1
	v_mfma_f32_16x16x32_bf16 v[60:63], v[142:145], v[158:161], v[60:63]
	v_mfma_f32_16x16x32_bf16 v[56:59], v[150:153], v[158:161], v[56:59]
	v_mfma_f32_16x16x32_bf16 v[52:55], v[142:145], v[166:169], v[52:55]
	v_mfma_f32_16x16x32_bf16 v[48:51], v[150:153], v[166:169], v[48:51]
	v_mfma_f32_16x16x32_bf16 v[36:39], v[142:145], v[182:185], v[36:39]
	v_mfma_f32_16x16x32_bf16 v[32:35], v[150:153], v[182:185], v[32:35]
	v_mfma_f32_16x16x32_bf16 v[20:23], v[142:145], v[194:197], v[20:23]
	v_mfma_f32_16x16x32_bf16 v[16:19], v[150:153], v[194:197], v[16:19]
	v_mfma_f32_16x16x32_bf16 v[60:63], v[146:149], v[162:165], v[60:63]
	v_mfma_f32_16x16x32_bf16 v[56:59], v[154:157], v[162:165], v[56:59]
	v_mfma_f32_16x16x32_bf16 v[52:55], v[146:149], v[170:173], v[52:55]
	v_mfma_f32_16x16x32_bf16 v[48:51], v[154:157], v[170:173], v[48:51]
	v_mfma_f32_16x16x32_bf16 v[36:39], v[146:149], v[190:193], v[36:39]
	v_mfma_f32_16x16x32_bf16 v[32:35], v[154:157], v[190:193], v[32:35]
	v_mfma_f32_16x16x32_bf16 v[20:23], v[146:149], v[198:201], v[20:23]
	v_mfma_f32_16x16x32_bf16 v[16:19], v[154:157], v[198:201], v[16:19]
	s_setprio 0
	s_barrier
	s_add_u32 s14, s14, 0x40080
	s_addc_u32 s15, s15, 0
	s_add_i32 s16, s16, s20
	s_mov_b32 m0, s16
	s_nop 0
	global_load_lds_dwordx4 v176, s[14:15]
	s_add_i32 m0, s16, 0x2000
	s_nop 0
	global_load_lds_dwordx4 v128, s[14:15]
	s_waitcnt vmcnt(6)
	s_barrier
	s_setprio 1
	v_mfma_f32_16x16x32_bf16 v[44:47], v[202:205], v[158:161], v[44:47]
	v_mfma_f32_16x16x32_bf16 v[40:43], v[210:213], v[158:161], v[40:43]
	v_mfma_f32_16x16x32_bf16 v[28:31], v[202:205], v[166:169], v[28:31]
	v_mfma_f32_16x16x32_bf16 v[24:27], v[210:213], v[166:169], v[24:27]
	v_mfma_f32_16x16x32_bf16 v[12:15], v[202:205], v[182:185], v[12:15]
	v_mfma_f32_16x16x32_bf16 v[8:11], v[210:213], v[182:185], v[8:11]
	v_mfma_f32_16x16x32_bf16 v[4:7], v[202:205], v[194:197], v[4:7]
	v_mfma_f32_16x16x32_bf16 v[0:3], v[210:213], v[194:197], v[0:3]
	v_mfma_f32_16x16x32_bf16 v[44:47], v[206:209], v[162:165], v[44:47]
	v_mfma_f32_16x16x32_bf16 v[40:43], v[214:217], v[162:165], v[40:43]
	v_mfma_f32_16x16x32_bf16 v[28:31], v[206:209], v[170:173], v[28:31]
	v_mfma_f32_16x16x32_bf16 v[24:27], v[214:217], v[170:173], v[24:27]
	v_mfma_f32_16x16x32_bf16 v[12:15], v[206:209], v[190:193], v[12:15]
	v_mfma_f32_16x16x32_bf16 v[8:11], v[214:217], v[190:193], v[8:11]
	v_mfma_f32_16x16x32_bf16 v[4:7], v[206:209], v[198:201], v[4:7]
	v_mfma_f32_16x16x32_bf16 v[0:3], v[214:217], v[198:201], v[0:3]
	s_setprio 0
	s_add_i32 s45, s45, 2
	s_add_u32 s12, s12, 0x100
	s_addc_u32 s13, s13, 0
	s_add_u32 s43, s43, 0x100
	s_addc_u32 s44, s44, 0
	s_cmp_gt_u32 s45, 13
	s_barrier
	s_cbranch_scc0 .LBB0_358
; __device__ __forceinline__ unsigned cvtpk(float lo, float hi) { const f32x2 v = (f32x2){lo, hi}; const bf16v2 b = __builtin_convertvector(v, bf16v2); return __builtin_bit_cast(unsigned, b); }
; #define PG8_WAIT_V(n) asm volatile("s_waitcnt vmcnt(" #n ")" ::: "memory")
; #define PG8_BAR __builtin_amdgcn_s_barrier()
; template <class Epi, class Sched>
; __device__ __forceinline__ void gemm_phase(PG8_LAS unsigned char* lds, const Gemm g, const Sched& S, const Epi& E) {
;     ...
;         if constexpr (!Epi::AFTER_DRAIN) { E(acc, cur, wr, wc, fr, fq); S.done(cur); }
;         if (!has_next) break;
; #pragma unroll
;         for (int a = 0; a < 2; ++a)
; #pragma unroll
;             for (int b = 0; b < 2; ++b)
; #pragma unroll
;                 for (int m = 0; m < 4; ++m)
; #pragma unroll
;                     for (int n = 0; n < 2; ++n) acc[a][b][m][n] = (f32x4){0.f, 0.f, 0.f, 0.f};
;         cur = nxt; cA = nA; cB = nB; ++ui;
;     }
;     PG8_WAIT_V(0);
;     if (wr == 0) PG8_BAR;
;     PG8_BAR;
;     __device__ __forceinline__ void operator()(const f32x4 (&acc)[2][2][4][2], const pg8::Unit& u, int wr, int wc, int fr, int fq) const {
;         const int row0 = u.pm * 256 + wr * 64 + fr, col0 = u.pn * 256 + wc * 32 + 8 * fq;
; #pragma unroll
;         for (int ai = 0; ai < 2; ++ai)
; #pragma unroll
;             for (int m = 0; m < 4; ++m) { bf16_t* rowp = O + (size_t)(row0 + ai * 128 + m * 16) * ldc + col0;
; #pragma unroll
;                 for (int bj = 0; bj < 2; ++bj) { const f32x4 v0 = acc[ai][bj][m][0], v1 = acc[ai][bj][m][1];
;                     u32x4 w; w.x = cvtpk(v0[0], v0[1]); w.y = cvtpk(v0[2], v0[3]); w.z = cvtpk(v1[0], v1[1]); w.w = cvtpk(v1[2], v1[3]);
;                     *(u32x4*)(rowp + bj * 128) = w; } }
	v_readlane_b32 s12, v253, 16
	v_lshl_add_u32 v148, s0, 8, v138
	v_lshl_or_b32 v142, s34, 8, v140
	v_readlane_b32 s13, v253, 17
	v_ashrrev_i32_e32 v143, 31, v142
	v_cvt_pk_bf16_f32 v68, v68, v69
	v_mov_b64_e32 v[144:145], s[12:13]
	v_cvt_pk_bf16_f32 v69, v70, v71
	v_cvt_pk_bf16_f32 v70, v64, v65
	v_add_u32_e32 v64, 0x80, v148
	v_mad_i64_i32 v[146:147], s[12:13], v148, s81, v[144:145]
	v_lshlrev_b64 v[142:143], 1, v[142:143]
	v_cvt_pk_bf16_f32 v108, v108, v109
	v_cvt_pk_bf16_f32 v109, v110, v111
	v_cvt_pk_bf16_f32 v110, v104, v105
	v_or_b32_e32 v104, 16, v148
	v_mad_i64_i32 v[64:65], s[12:13], v64, s81, v[144:145]
	v_cvt_pk_bf16_f32 v44, v44, v45
	v_cvt_pk_bf16_f32 v45, v46, v47
	v_cvt_pk_bf16_f32 v46, v40, v41
	v_add_u32_e32 v40, 0x90, v148
	v_lshl_add_u64 v[146:147], v[146:147], 0, v[142:143]
	v_cvt_pk_bf16_f32 v111, v106, v107
	v_mad_i64_i32 v[104:105], s[12:13], v104, s81, v[144:145]
	v_cvt_pk_bf16_f32 v92, v92, v93
	v_cvt_pk_bf16_f32 v93, v94, v95
	v_cvt_pk_bf16_f32 v94, v88, v89
	v_or_b32_e32 v88, 32, v148
	v_lshl_add_u64 v[64:65], v[64:65], 0, v[142:143]
	v_cvt_pk_bf16_f32 v47, v42, v43
	v_mad_i64_i32 v[40:41], s[12:13], v40, s81, v[144:145]
	v_cvt_pk_bf16_f32 v28, v28, v29
	v_cvt_pk_bf16_f32 v29, v30, v31
	v_cvt_pk_bf16_f32 v30, v24, v25
	v_add_u32_e32 v24, 0xa0, v148
	global_store_dwordx4 v[146:147], v[108:111], off offset:256
	v_cvt_pk_bf16_f32 v95, v90, v91
	v_mad_i64_i32 v[88:89], s[12:13], v88, s81, v[144:145]
	v_lshl_add_u64 v[108:109], v[104:105], 0, v[142:143]
	v_cvt_pk_bf16_f32 v76, v76, v77
	v_cvt_pk_bf16_f32 v77, v78, v79
	v_cvt_pk_bf16_f32 v78, v72, v73
	v_or_b32_e32 v72, 48, v148
	global_store_dwordx4 v[64:65], v[44:47], off offset:256
	v_cvt_pk_bf16_f32 v31, v26, v27
	v_mad_i64_i32 v[24:25], s[12:13], v24, s81, v[144:145]
	v_lshl_add_u64 v[44:45], v[40:41], 0, v[142:143]
	v_cvt_pk_bf16_f32 v12, v12, v13
	v_cvt_pk_bf16_f32 v13, v14, v15
	v_cvt_pk_bf16_f32 v14, v8, v9
	v_add_u32_e32 v8, 0xb0, v148
	global_store_dwordx4 v[108:109], v[92:95], off offset:256
	v_cvt_pk_bf16_f32 v79, v74, v75
	v_mad_i64_i32 v[72:73], s[12:13], v72, s81, v[144:145]
	v_lshl_add_u64 v[92:93], v[88:89], 0, v[142:143]
	global_store_dwordx4 v[44:45], v[28:31], off offset:256
	v_cvt_pk_bf16_f32 v15, v10, v11
	v_mad_i64_i32 v[8:9], s[12:13], v8, s81, v[144:145]
	v_lshl_add_u64 v[28:29], v[24:25], 0, v[142:143]
	v_cvt_pk_bf16_f32 v124, v124, v125
	v_cvt_pk_bf16_f32 v125, v126, v127
	v_cvt_pk_bf16_f32 v126, v120, v121
	v_cvt_pk_bf16_f32 v127, v122, v123
	v_cvt_pk_bf16_f32 v104, v116, v117
	v_cvt_pk_bf16_f32 v105, v118, v119
	v_cvt_pk_bf16_f32 v106, v112, v113
	v_cvt_pk_bf16_f32 v107, v114, v115
	v_cvt_pk_bf16_f32 v88, v100, v101
	v_cvt_pk_bf16_f32 v89, v102, v103
	v_cvt_pk_bf16_f32 v90, v96, v97
	v_cvt_pk_bf16_f32 v91, v98, v99
	global_store_dwordx4 v[92:93], v[76:79], off offset:256
	v_cvt_pk_bf16_f32 v74, v80, v81
	v_cvt_pk_bf16_f32 v75, v82, v83
	v_lshl_add_u64 v[76:77], v[72:73], 0, v[142:143]
	v_cvt_pk_bf16_f32 v72, v84, v85
	v_cvt_pk_bf16_f32 v73, v86, v87
	v_cvt_pk_bf16_f32 v71, v66, v67
	v_cvt_pk_bf16_f32 v60, v60, v61
	v_cvt_pk_bf16_f32 v61, v62, v63
	v_cvt_pk_bf16_f32 v62, v56, v57
	v_cvt_pk_bf16_f32 v63, v58, v59
	v_cvt_pk_bf16_f32 v40, v52, v53
	v_cvt_pk_bf16_f32 v41, v54, v55
	v_cvt_pk_bf16_f32 v42, v48, v49
	v_cvt_pk_bf16_f32 v43, v50, v51
	v_cvt_pk_bf16_f32 v24, v36, v37
	v_cvt_pk_bf16_f32 v25, v38, v39
	v_cvt_pk_bf16_f32 v26, v32, v33
	v_cvt_pk_bf16_f32 v27, v34, v35
	global_store_dwordx4 v[28:29], v[12:15], off offset:256
	v_cvt_pk_bf16_f32 v10, v16, v17
	v_cvt_pk_bf16_f32 v11, v18, v19
	v_lshl_add_u64 v[12:13], v[8:9], 0, v[142:143]
	v_cvt_pk_bf16_f32 v8, v20, v21
	v_cvt_pk_bf16_f32 v9, v22, v23
	v_cvt_pk_bf16_f32 v4, v4, v5
	v_cvt_pk_bf16_f32 v5, v6, v7
	v_cvt_pk_bf16_f32 v6, v0, v1
	v_cvt_pk_bf16_f32 v7, v2, v3
	s_and_b64 vcc, exec, s[38:39]
	s_mov_b32 s34, s4
	s_mov_b32 s0, s6
	s_mov_b64 s[14:15], s[10:11]
	s_mov_b64 s[12:13], s[8:9]
	global_store_dwordx4 v[146:147], v[124:127], off
	global_store_dwordx4 v[108:109], v[104:107], off
	global_store_dwordx4 v[92:93], v[88:91], off
	global_store_dwordx4 v[76:77], v[72:75], off
	global_store_dwordx4 v[76:77], v[68:71], off offset:256
	global_store_dwordx4 v[64:65], v[60:63], off
	global_store_dwordx4 v[44:45], v[40:43], off
	global_store_dwordx4 v[28:29], v[24:27], off
	global_store_dwordx4 v[12:13], v[8:11], off
	global_store_dwordx4 v[12:13], v[4:7], off offset:256
	s_cbranch_vccz .LBB0_355
	s_waitcnt vmcnt(0)
	v_readlane_b32 s22, v255, 14
	s_cmpk_gt_u32 s19, 0xff
	v_readlane_b32 s23, v255, 15
	s_mov_b64 s[28:29], s[54:55]
	s_cbranch_scc1 .LBB0_362
	s_barrier
